# v23 + up-projection epilogue: conv bias/tap and tanh-gelu plain f32 steps issued as packed v_pk_* pairs (same per-element operations and order)
# baseline (speedup 1.0000x reference)
; #define PG8_LAS __attribute__((address_space(3)))
;     __device__ __forceinline__ void operator()(const f32x4 (&acc)[2][2][4][2], const Unit& u, int wr, int wc, int fr, int fq) const {
;         const int cl = wc * 32 + 8 * fq, cgc = u.pn * 128 + cl; const bool samp = u.pm >= 64;
;         f32x4 cw0[2], cw1[2], cw2[2], cb[2];
; #pragma unroll
;         for (int n = 0; n < 2; ++n) { cw0[n] = *(const f32x4*)(conv_w + cgc + 4 * n); cw1[n] = *(const f32x4*)(conv_w + DFF + cgc + 4 * n); cw2[n] = *(const f32x4*)(conv_w + 2 * DFF + cgc + 4 * n); cb[n] = *(const f32x4*)(conv_b + cgc + 4 * n); }
;         if (!samp) {
;             if (fr >= 14) {
; #pragma unroll
;                 for (int ai = 0; ai < 2; ++ai)
; #pragma unroll
;                     for (int n = 0; n < 2; ++n) *(PG8_LAS f32x4*)(xbuf + ((ai * 2 + wr) * 2 + (fr - 14)) * 128 + cl + 4 * n) = acc[ai][0][3][n];
;             }
;             asm volatile("s_waitcnt lgkmcnt(0)" ::: "memory"); __builtin_amdgcn_s_barrier(); asm volatile("" ::: "memory");
;         }
; #pragma unroll
;         for (int ai = 0; ai < 2; ++ai) { const int blk = ai * 2 + wr;
; #pragma unroll
;             for (int m = 0; m < 4; ++m) {
;                 const int row = u.pm * BM + ai * HALF + wr * 64 + m * 16 + fr;
;                 f32x4 w1[2], w2[2];
;                 if (samp) {
;                     const int bs = (row - MP) >> 4;
; #pragma unroll
;                     for (int n = 0; n < 2; ++n) { const f32x4 s0 = *(const f32x4*)(state + ((size_t)bs * 2 + 0) * DFF + cgc + 4 * n), s1 = *(const f32x4*)(state + ((size_t)bs * 2 + 1) * DFF + cgc + 4 * n);
;                         w1[n] = s1; w2[n] = fr == 0 ? s0 : s1; }
;                 } else if (m == 0) {
;                     if (blk > 0) {
; #pragma unroll
;                         for (int n = 0; n < 2; ++n) { const f32x4 c14 = *(const PG8_LAS f32x4*)(xbuf + ((blk - 1) * 2 + 0) * 128 + cl + 4 * n), c15 = *(const PG8_LAS f32x4*)(xbuf + ((blk - 1) * 2 + 1) * 128 + cl + 4 * n);
.LBB0_1229:
	s_mov_b32 s56, s22
	v_mov_b32_e32 v226, 0x3d372713
	v_mov_b32_e32 v228, 0x3fcc422a
	v_mov_b32_e32 v230, 0x3fb8aa3b
	s_mov_b32 s57, s67
	v_readlane_b32 s58, v251, 21
	v_readlane_b32 s76, v251, 26
	v_readlane_b32 s77, v251, 27
	v_readlane_b32 s78, v250, 4
	v_readlane_b32 s79, v250, 5
	v_readlane_b32 s60, v251, 46
	v_readlane_b32 s61, v251, 47
	v_readlane_b32 s66, v251, 62
	v_readlane_b32 s67, v251, 63
	v_bfe_u32 v214, v1, 4, 2
	v_bfe_u32 v215, v1, 6, 2
	v_lshlrev_b32_e32 v214, 3, v214
	v_lshl_add_u32 v214, v215, 5, v214
	v_and_b32_e32 v216, 15, v1
	v_and_b32_e32 v217, 1, v1
	s_lshr_b32 s58, s58, 2
	v_lshl_add_u32 v194, s57, 7, v214
	v_lshlrev_b32_e32 v194, 2, v194
	v_lshl_add_u32 v196, v217, 15, v194
	s_lshl_b32 s59, s56, 8
	s_lshl_b32 s31, s58, 6
	s_add_u32 s59, s59, s31
	v_add_u32_e32 v218, s59, v216
	v_lshlrev_b32_e32 v195, 14, v218
	v_lshrrev_b32_e32 v219, 1, v194
	v_add_u32_e32 v195, v195, v219
	v_lshlrev_b32_e32 v197, 9, v217
	v_lshl_add_u32 v197, v214, 2, v197
	s_lshl_b32 s31, s58, 10
	s_add_u32 s31, s31, 0x20000
	v_add_u32_e32 v197, s31, v197
	s_add_u32 s62, s60, 0x8000
	s_addc_u32 s63, s61, 0
	s_add_u32 s64, s60, 0x10000
	s_addc_u32 s65, s61, 0
	s_add_u32 s70, s76, 0xdb00000
	s_addc_u32 s71, s77, 0
	global_load_dwordx4 v[42:45], v194, s[60:61]
	global_load_dwordx4 v[46:49], v194, s[60:61] offset:16
	global_load_dwordx4 v[50:53], v194, s[62:63]
	global_load_dwordx4 v[54:57], v194, s[62:63] offset:16
	global_load_dwordx4 v[66:69], v194, s[64:65]
	global_load_dwordx4 v[70:73], v194, s[64:65] offset:16
	global_load_dwordx4 v[74:77], v194, s[66:67]
	global_load_dwordx4 v[78:81], v194, s[66:67] offset:16
	s_cmp_gt_i32 s56, 63
	s_cbranch_scc1 .Lup_samp
	s_mov_b32 exec_lo, 0xc000c000
	s_mov_b32 exec_hi, 0xc000c000
	ds_write_b128 v197, v[102:105]
	ds_write_b128 v197, v[98:101] offset:16
	ds_write_b128 v197, v[6:9] offset:2048
	ds_write_b128 v197, v[2:5] offset:2064
	s_mov_b64 exec, -1
	s_waitcnt lgkmcnt(0)
	s_barrier
	s_waitcnt vmcnt(0)
	s_cmp_eq_u32 s58, 0
	s_cbranch_scc1 .Lup_p00_zero
	v_add_u32_e32 v223, 0xfffffc00, v197
	ds_read_b128 v[162:165], v223
	ds_read_b128 v[166:169], v223 offset:16
	s_waitcnt lgkmcnt(0)
	s_branch .Lup_p00_go

; __device__ __forceinline__ u32x4 pack8(const f32x4 a, const f32x4 b) { u32x4 w; w.x = cvt_pk_bf16(a[0], a[1]); w.y = cvt_pk_bf16(a[2], a[3]); w.z = cvt_pk_bf16(b[0], b[1]); w.w = cvt_pk_bf16(b[2], b[3]); return w; }
; template <int CTRL> __device__ __forceinline__ float dppf(float v) { return __builtin_bit_cast(float, __builtin_amdgcn_update_dpp(0, __builtin_bit_cast(int, v), CTRL, 0xf, 0xf, true)); }
; __device__ __forceinline__ float gelu_tanh(float x) {
;     const float u2 = 1.5957691216057308f * x * (1.0f + 0.044715f * x * x);
;     return x * __builtin_amdgcn_rcpf(1.0f + __builtin_amdgcn_exp2f(-u2 * LOG2E));
; }
;     __device__ __forceinline__ void operator()(const f32x4 (&acc)[2][2][4][2], const Unit& u, int wr, int wc, int fr, int fq) const {
;     ...
;                 f32x4 hv[2];
; #pragma unroll
;                 for (int n = 0; n < 2; ++n) {
;                     const f32x4 a = acc[ai][0][m][n], b = acc[ai][1][m][n];
; #pragma unroll
;                     for (int i = 0; i < 4; ++i) {
;                         const float s1 = dppf<0x111>(a[i]), s2 = dppf<0x112>(a[i]);
;                         const float p1 = fr >= 1 ? s1 : w1[n][i], p2 = fr >= 2 ? s2 : w2[n][i];
;                         const float ac = cw0[n][i] * p2 + cw1[n][i] * p1 + cw2[n][i] * a[i] + cb[n][i];
;                         hv[n][i] = gelu_tanh(ac) * b[i];
;                     }
;                 }
;                 *(u32x4*)(hh + (size_t)row * DFF + cgc) = pack8(hv[0], hv[1]);
.Lup_p00_go:
	v_pk_fma_f32 v[214:215], v[66:67], v[150:151], v[74:75]
	v_pk_fma_f32 v[216:217], v[68:69], v[152:153], v[76:77]
	v_fmac_f32_dpp v214, v150, v50 row_shr:1 row_mask:0xf bank_mask:0xf
	v_fmac_f32_dpp v215, v151, v51 row_shr:1 row_mask:0xf bank_mask:0xf
	v_fmac_f32_dpp v216, v152, v52 row_shr:1 row_mask:0xf bank_mask:0xf
	v_fmac_f32_dpp v217, v153, v53 row_shr:1 row_mask:0xf bank_mask:0xf
	v_fmac_f32_dpp v214, v162, v50 row_shl:15 row_mask:0xf bank_mask:0xf
	v_fmac_f32_dpp v215, v163, v51 row_shl:15 row_mask:0xf bank_mask:0xf
	v_fmac_f32_dpp v216, v164, v52 row_shl:15 row_mask:0xf bank_mask:0xf
	v_fmac_f32_dpp v217, v165, v53 row_shl:15 row_mask:0xf bank_mask:0xf
	v_fmac_f32_dpp v214, v150, v42 row_shr:2 row_mask:0xf bank_mask:0xf
	v_fmac_f32_dpp v215, v151, v43 row_shr:2 row_mask:0xf bank_mask:0xf
	v_fmac_f32_dpp v216, v152, v44 row_shr:2 row_mask:0xf bank_mask:0xf
	v_fmac_f32_dpp v217, v153, v45 row_shr:2 row_mask:0xf bank_mask:0xf
	v_fmac_f32_dpp v214, v162, v42 row_shl:14 row_mask:0xf bank_mask:0xf
	v_fmac_f32_dpp v215, v163, v43 row_shl:14 row_mask:0xf bank_mask:0xf
	v_fmac_f32_dpp v216, v164, v44 row_shl:14 row_mask:0xf bank_mask:0xf
	v_fmac_f32_dpp v217, v165, v45 row_shl:14 row_mask:0xf bank_mask:0xf
	v_pk_mul_f32 v[218:219], v[214:215], v[226:227] op_sel_hi:[1,0]
	v_pk_mul_f32 v[220:221], v[216:217], v[226:227] op_sel_hi:[1,0]
	v_pk_mul_f32 v[222:223], v[214:215], v[228:229] op_sel_hi:[1,0]
	v_pk_mul_f32 v[224:225], v[216:217], v[228:229] op_sel_hi:[1,0]
	v_pk_fma_f32 v[218:219], v[214:215], v[218:219], 1.0 op_sel_hi:[1,1,0]
	v_pk_fma_f32 v[220:221], v[216:217], v[220:221], 1.0 op_sel_hi:[1,1,0]
	v_pk_mul_f32 v[222:223], v[222:223], v[218:219] neg_lo:[0,1] neg_hi:[0,1]
	v_pk_mul_f32 v[224:225], v[224:225], v[220:221] neg_lo:[0,1] neg_hi:[0,1]
	v_pk_mul_f32 v[222:223], v[222:223], v[230:231] op_sel_hi:[1,0]
	v_pk_mul_f32 v[224:225], v[224:225], v[230:231] op_sel_hi:[1,0]
	v_exp_f32_e32 v222, v222
	v_exp_f32_e32 v223, v223
	v_exp_f32_e32 v224, v224
	v_exp_f32_e32 v225, v225
	v_pk_add_f32 v[222:223], v[222:223], 1.0 op_sel_hi:[1,0]
	v_pk_add_f32 v[224:225], v[224:225], 1.0 op_sel_hi:[1,0]
	v_rcp_f32_e32 v222, v222
	v_rcp_f32_e32 v223, v223
	v_rcp_f32_e32 v224, v224
	v_rcp_f32_e32 v225, v225
	v_pk_mul_f32 v[218:219], v[214:215], v[222:223]
	v_pk_mul_f32 v[220:221], v[216:217], v[224:225]
	v_pk_mul_f32 v[158:159], v[158:159], v[218:219]
	v_pk_mul_f32 v[160:161], v[160:161], v[220:221]
	v_pk_fma_f32 v[214:215], v[70:71], v[146:147], v[78:79]
	v_pk_fma_f32 v[216:217], v[72:73], v[148:149], v[80:81]
	v_fmac_f32_dpp v214, v146, v54 row_shr:1 row_mask:0xf bank_mask:0xf
	v_fmac_f32_dpp v215, v147, v55 row_shr:1 row_mask:0xf bank_mask:0xf
	v_fmac_f32_dpp v216, v148, v56 row_shr:1 row_mask:0xf bank_mask:0xf
	v_fmac_f32_dpp v217, v149, v57 row_shr:1 row_mask:0xf bank_mask:0xf
	v_fmac_f32_dpp v214, v166, v54 row_shl:15 row_mask:0xf bank_mask:0xf
	v_fmac_f32_dpp v215, v167, v55 row_shl:15 row_mask:0xf bank_mask:0xf
	v_fmac_f32_dpp v216, v168, v56 row_shl:15 row_mask:0xf bank_mask:0xf
	v_fmac_f32_dpp v217, v169, v57 row_shl:15 row_mask:0xf bank_mask:0xf
	v_fmac_f32_dpp v214, v146, v46 row_shr:2 row_mask:0xf bank_mask:0xf
	v_fmac_f32_dpp v215, v147, v47 row_shr:2 row_mask:0xf bank_mask:0xf
	v_fmac_f32_dpp v216, v148, v48 row_shr:2 row_mask:0xf bank_mask:0xf
	v_fmac_f32_dpp v217, v149, v49 row_shr:2 row_mask:0xf bank_mask:0xf
	v_fmac_f32_dpp v214, v166, v46 row_shl:14 row_mask:0xf bank_mask:0xf
	v_fmac_f32_dpp v215, v167, v47 row_shl:14 row_mask:0xf bank_mask:0xf
	v_fmac_f32_dpp v216, v168, v48 row_shl:14 row_mask:0xf bank_mask:0xf
	v_fmac_f32_dpp v217, v169, v49 row_shl:14 row_mask:0xf bank_mask:0xf
	v_pk_mul_f32 v[218:219], v[214:215], v[226:227] op_sel_hi:[1,0]
	v_pk_mul_f32 v[220:221], v[216:217], v[226:227] op_sel_hi:[1,0]
	v_pk_mul_f32 v[222:223], v[214:215], v[228:229] op_sel_hi:[1,0]
	v_pk_mul_f32 v[224:225], v[216:217], v[228:229] op_sel_hi:[1,0]
	v_pk_fma_f32 v[218:219], v[214:215], v[218:219], 1.0 op_sel_hi:[1,1,0]
	v_pk_fma_f32 v[220:221], v[216:217], v[220:221], 1.0 op_sel_hi:[1,1,0]
	v_pk_mul_f32 v[222:223], v[222:223], v[218:219] neg_lo:[0,1] neg_hi:[0,1]
	v_pk_mul_f32 v[224:225], v[224:225], v[220:221] neg_lo:[0,1] neg_hi:[0,1]
	v_pk_mul_f32 v[222:223], v[222:223], v[230:231] op_sel_hi:[1,0]
	v_pk_mul_f32 v[224:225], v[224:225], v[230:231] op_sel_hi:[1,0]
	v_exp_f32_e32 v222, v222
	v_exp_f32_e32 v223, v223
	v_exp_f32_e32 v224, v224
	v_exp_f32_e32 v225, v225
	v_pk_add_f32 v[222:223], v[222:223], 1.0 op_sel_hi:[1,0]
	v_pk_add_f32 v[224:225], v[224:225], 1.0 op_sel_hi:[1,0]
	v_rcp_f32_e32 v222, v222
	v_rcp_f32_e32 v223, v223
	v_rcp_f32_e32 v224, v224
	v_rcp_f32_e32 v225, v225
	v_pk_mul_f32 v[218:219], v[214:215], v[222:223]
	v_pk_mul_f32 v[220:221], v[216:217], v[224:225]
	v_pk_mul_f32 v[154:155], v[154:155], v[218:219]
	v_pk_mul_f32 v[156:157], v[156:157], v[220:221]
	v_cvt_pk_bf16_f32 v158, v158, v159
	v_cvt_pk_bf16_f32 v159, v160, v161
	v_cvt_pk_bf16_f32 v160, v154, v155
	v_cvt_pk_bf16_f32 v161, v156, v157
	v_mov_b32_e32 v222, v195
	global_store_dwordx4 v222, v[158:161], s[70:71]
	v_pk_fma_f32 v[214:215], v[66:67], v[134:135], v[74:75]
	v_pk_fma_f32 v[216:217], v[68:69], v[136:137], v[76:77]
	v_fmac_f32_dpp v214, v134, v50 row_shr:1 row_mask:0xf bank_mask:0xf
	v_fmac_f32_dpp v215, v135, v51 row_shr:1 row_mask:0xf bank_mask:0xf
	v_fmac_f32_dpp v216, v136, v52 row_shr:1 row_mask:0xf bank_mask:0xf
	v_fmac_f32_dpp v217, v137, v53 row_shr:1 row_mask:0xf bank_mask:0xf
	v_fmac_f32_dpp v214, v150, v50 row_shl:15 row_mask:0xf bank_mask:0xf
	v_fmac_f32_dpp v215, v151, v51 row_shl:15 row_mask:0xf bank_mask:0xf
; __device__ __forceinline__ u32x4 pack8(const f32x4 a, const f32x4 b) { u32x4 w; w.x = cvt_pk_bf16(a[0], a[1]); w.y = cvt_pk_bf16(a[2], a[3]); w.z = cvt_pk_bf16(b[0], b[1]); w.w = cvt_pk_bf16(b[2], b[3]); return w; }
; template <int CTRL> __device__ __forceinline__ float dppf(float v) { return __builtin_bit_cast(float, __builtin_amdgcn_update_dpp(0, __builtin_bit_cast(int, v), CTRL, 0xf, 0xf, true)); }
; __device__ __forceinline__ float gelu_tanh(float x) {
;     const float u2 = 1.5957691216057308f * x * (1.0f + 0.044715f * x * x);
;     return x * __builtin_amdgcn_rcpf(1.0f + __builtin_amdgcn_exp2f(-u2 * LOG2E));
; }
;     __device__ __forceinline__ void operator()(const f32x4 (&acc)[2][2][4][2], const Unit& u, int wr, int wc, int fr, int fq) const {
;     ...
;                 f32x4 hv[2];
; #pragma unroll
;                 for (int n = 0; n < 2; ++n) {
;                     const f32x4 a = acc[ai][0][m][n], b = acc[ai][1][m][n];
; #pragma unroll
;                     for (int i = 0; i < 4; ++i) {
;                         const float s1 = dppf<0x111>(a[i]), s2 = dppf<0x112>(a[i]);
;                         const float p1 = fr >= 1 ? s1 : w1[n][i], p2 = fr >= 2 ? s2 : w2[n][i];
;                         const float ac = cw0[n][i] * p2 + cw1[n][i] * p1 + cw2[n][i] * a[i] + cb[n][i];
;                         hv[n][i] = gelu_tanh(ac) * b[i];
;                     }
;                 }
;                 *(u32x4*)(hh + (size_t)row * DFF + cgc) = pack8(hv[0], hv[1]);
	v_fmac_f32_dpp v216, v152, v52 row_shl:15 row_mask:0xf bank_mask:0xf
	v_fmac_f32_dpp v217, v153, v53 row_shl:15 row_mask:0xf bank_mask:0xf
	v_fmac_f32_dpp v214, v134, v42 row_shr:2 row_mask:0xf bank_mask:0xf
	v_fmac_f32_dpp v215, v135, v43 row_shr:2 row_mask:0xf bank_mask:0xf
	v_fmac_f32_dpp v216, v136, v44 row_shr:2 row_mask:0xf bank_mask:0xf
	v_fmac_f32_dpp v217, v137, v45 row_shr:2 row_mask:0xf bank_mask:0xf
	v_fmac_f32_dpp v214, v150, v42 row_shl:14 row_mask:0xf bank_mask:0xf
	v_fmac_f32_dpp v215, v151, v43 row_shl:14 row_mask:0xf bank_mask:0xf
	v_fmac_f32_dpp v216, v152, v44 row_shl:14 row_mask:0xf bank_mask:0xf
	v_fmac_f32_dpp v217, v153, v45 row_shl:14 row_mask:0xf bank_mask:0xf
	v_pk_mul_f32 v[218:219], v[214:215], v[226:227] op_sel_hi:[1,0]
	v_pk_mul_f32 v[220:221], v[216:217], v[226:227] op_sel_hi:[1,0]
	v_pk_mul_f32 v[222:223], v[214:215], v[228:229] op_sel_hi:[1,0]
	v_pk_mul_f32 v[224:225], v[216:217], v[228:229] op_sel_hi:[1,0]
	v_pk_fma_f32 v[218:219], v[214:215], v[218:219], 1.0 op_sel_hi:[1,1,0]
	v_pk_fma_f32 v[220:221], v[216:217], v[220:221], 1.0 op_sel_hi:[1,1,0]
	v_pk_mul_f32 v[222:223], v[222:223], v[218:219] neg_lo:[0,1] neg_hi:[0,1]
	v_pk_mul_f32 v[224:225], v[224:225], v[220:221] neg_lo:[0,1] neg_hi:[0,1]
	v_pk_mul_f32 v[222:223], v[222:223], v[230:231] op_sel_hi:[1,0]
	v_pk_mul_f32 v[224:225], v[224:225], v[230:231] op_sel_hi:[1,0]
	v_exp_f32_e32 v222, v222
	v_exp_f32_e32 v223, v223
	v_exp_f32_e32 v224, v224
	v_exp_f32_e32 v225, v225
	v_pk_add_f32 v[222:223], v[222:223], 1.0 op_sel_hi:[1,0]
	v_pk_add_f32 v[224:225], v[224:225], 1.0 op_sel_hi:[1,0]
	v_rcp_f32_e32 v222, v222
	v_rcp_f32_e32 v223, v223
	v_rcp_f32_e32 v224, v224
	v_rcp_f32_e32 v225, v225
	v_pk_mul_f32 v[218:219], v[214:215], v[222:223]
	v_pk_mul_f32 v[220:221], v[216:217], v[224:225]
	v_pk_mul_f32 v[142:143], v[142:143], v[218:219]
	v_pk_mul_f32 v[144:145], v[144:145], v[220:221]
	v_pk_fma_f32 v[214:215], v[70:71], v[130:131], v[78:79]
	v_pk_fma_f32 v[216:217], v[72:73], v[132:133], v[80:81]
	v_fmac_f32_dpp v214, v130, v54 row_shr:1 row_mask:0xf bank_mask:0xf
	v_fmac_f32_dpp v215, v131, v55 row_shr:1 row_mask:0xf bank_mask:0xf
	v_fmac_f32_dpp v216, v132, v56 row_shr:1 row_mask:0xf bank_mask:0xf
	v_fmac_f32_dpp v217, v133, v57 row_shr:1 row_mask:0xf bank_mask:0xf
	v_fmac_f32_dpp v214, v146, v54 row_shl:15 row_mask:0xf bank_mask:0xf
	v_fmac_f32_dpp v215, v147, v55 row_shl:15 row_mask:0xf bank_mask:0xf
	v_fmac_f32_dpp v216, v148, v56 row_shl:15 row_mask:0xf bank_mask:0xf
	v_fmac_f32_dpp v217, v149, v57 row_shl:15 row_mask:0xf bank_mask:0xf
	v_fmac_f32_dpp v214, v130, v46 row_shr:2 row_mask:0xf bank_mask:0xf
	v_fmac_f32_dpp v215, v131, v47 row_shr:2 row_mask:0xf bank_mask:0xf
	v_fmac_f32_dpp v216, v132, v48 row_shr:2 row_mask:0xf bank_mask:0xf
	v_fmac_f32_dpp v217, v133, v49 row_shr:2 row_mask:0xf bank_mask:0xf
	v_fmac_f32_dpp v214, v146, v46 row_shl:14 row_mask:0xf bank_mask:0xf
	v_fmac_f32_dpp v215, v147, v47 row_shl:14 row_mask:0xf bank_mask:0xf
	v_fmac_f32_dpp v216, v148, v48 row_shl:14 row_mask:0xf bank_mask:0xf
	v_fmac_f32_dpp v217, v149, v49 row_shl:14 row_mask:0xf bank_mask:0xf
	v_pk_mul_f32 v[218:219], v[214:215], v[226:227] op_sel_hi:[1,0]
	v_pk_mul_f32 v[220:221], v[216:217], v[226:227] op_sel_hi:[1,0]
	v_pk_mul_f32 v[222:223], v[214:215], v[228:229] op_sel_hi:[1,0]
	v_pk_mul_f32 v[224:225], v[216:217], v[228:229] op_sel_hi:[1,0]
	v_pk_fma_f32 v[218:219], v[214:215], v[218:219], 1.0 op_sel_hi:[1,1,0]
	v_pk_fma_f32 v[220:221], v[216:217], v[220:221], 1.0 op_sel_hi:[1,1,0]
	v_pk_mul_f32 v[222:223], v[222:223], v[218:219] neg_lo:[0,1] neg_hi:[0,1]
	v_pk_mul_f32 v[224:225], v[224:225], v[220:221] neg_lo:[0,1] neg_hi:[0,1]
	v_pk_mul_f32 v[222:223], v[222:223], v[230:231] op_sel_hi:[1,0]
	v_pk_mul_f32 v[224:225], v[224:225], v[230:231] op_sel_hi:[1,0]
	v_exp_f32_e32 v222, v222
	v_exp_f32_e32 v223, v223
	v_exp_f32_e32 v224, v224
	v_exp_f32_e32 v225, v225
	v_pk_add_f32 v[222:223], v[222:223], 1.0 op_sel_hi:[1,0]
	v_pk_add_f32 v[224:225], v[224:225], 1.0 op_sel_hi:[1,0]
	v_rcp_f32_e32 v222, v222
	v_rcp_f32_e32 v223, v223
	v_rcp_f32_e32 v224, v224
	v_rcp_f32_e32 v225, v225
	v_pk_mul_f32 v[218:219], v[214:215], v[222:223]
	v_pk_mul_f32 v[220:221], v[216:217], v[224:225]
	v_pk_mul_f32 v[138:139], v[138:139], v[218:219]
	v_pk_mul_f32 v[140:141], v[140:141], v[220:221]
	v_cvt_pk_bf16_f32 v142, v142, v143
	v_cvt_pk_bf16_f32 v143, v144, v145
	v_cvt_pk_bf16_f32 v144, v138, v139
	v_cvt_pk_bf16_f32 v145, v140, v141
	v_add_u32_e32 v222, 0x40000, v195
	global_store_dwordx4 v222, v[142:145], s[70:71]
	v_pk_fma_f32 v[214:215], v[66:67], v[118:119], v[74:75]
	v_pk_fma_f32 v[216:217], v[68:69], v[120:121], v[76:77]
	v_fmac_f32_dpp v214, v118, v50 row_shr:1 row_mask:0xf bank_mask:0xf
	v_fmac_f32_dpp v215, v119, v51 row_shr:1 row_mask:0xf bank_mask:0xf
	v_fmac_f32_dpp v216, v120, v52 row_shr:1 row_mask:0xf bank_mask:0xf
	v_fmac_f32_dpp v217, v121, v53 row_shr:1 row_mask:0xf bank_mask:0xf
	v_fmac_f32_dpp v214, v134, v50 row_shl:15 row_mask:0xf bank_mask:0xf
	v_fmac_f32_dpp v215, v135, v51 row_shl:15 row_mask:0xf bank_mask:0xf
	v_fmac_f32_dpp v216, v136, v52 row_shl:15 row_mask:0xf bank_mask:0xf
	v_fmac_f32_dpp v217, v137, v53 row_shl:15 row_mask:0xf bank_mask:0xf
	v_fmac_f32_dpp v214, v118, v42 row_shr:2 row_mask:0xf bank_mask:0xf
	v_fmac_f32_dpp v215, v119, v43 row_shr:2 row_mask:0xf bank_mask:0xf
	v_fmac_f32_dpp v216, v120, v44 row_shr:2 row_mask:0xf bank_mask:0xf
	v_fmac_f32_dpp v217, v121, v45 row_shr:2 row_mask:0xf bank_mask:0xf
	v_fmac_f32_dpp v214, v134, v42 row_shl:14 row_mask:0xf bank_mask:0xf
	v_fmac_f32_dpp v215, v135, v43 row_shl:14 row_mask:0xf bank_mask:0xf
; __device__ __forceinline__ u32x4 pack8(const f32x4 a, const f32x4 b) { u32x4 w; w.x = cvt_pk_bf16(a[0], a[1]); w.y = cvt_pk_bf16(a[2], a[3]); w.z = cvt_pk_bf16(b[0], b[1]); w.w = cvt_pk_bf16(b[2], b[3]); return w; }
; template <int CTRL> __device__ __forceinline__ float dppf(float v) { return __builtin_bit_cast(float, __builtin_amdgcn_update_dpp(0, __builtin_bit_cast(int, v), CTRL, 0xf, 0xf, true)); }
; __device__ __forceinline__ float gelu_tanh(float x) {
;     const float u2 = 1.5957691216057308f * x * (1.0f + 0.044715f * x * x);
;     return x * __builtin_amdgcn_rcpf(1.0f + __builtin_amdgcn_exp2f(-u2 * LOG2E));
; }
;     __device__ __forceinline__ void operator()(const f32x4 (&acc)[2][2][4][2], const Unit& u, int wr, int wc, int fr, int fq) const {
;     ...
;                 f32x4 hv[2];
; #pragma unroll
;                 for (int n = 0; n < 2; ++n) {
;                     const f32x4 a = acc[ai][0][m][n], b = acc[ai][1][m][n];
; #pragma unroll
;                     for (int i = 0; i < 4; ++i) {
;                         const float s1 = dppf<0x111>(a[i]), s2 = dppf<0x112>(a[i]);
;                         const float p1 = fr >= 1 ? s1 : w1[n][i], p2 = fr >= 2 ? s2 : w2[n][i];
;                         const float ac = cw0[n][i] * p2 + cw1[n][i] * p1 + cw2[n][i] * a[i] + cb[n][i];
;                         hv[n][i] = gelu_tanh(ac) * b[i];
;                     }
;                 }
;                 *(u32x4*)(hh + (size_t)row * DFF + cgc) = pack8(hv[0], hv[1]);
	v_fmac_f32_dpp v216, v136, v44 row_shl:14 row_mask:0xf bank_mask:0xf
	v_fmac_f32_dpp v217, v137, v45 row_shl:14 row_mask:0xf bank_mask:0xf
	v_pk_mul_f32 v[218:219], v[214:215], v[226:227] op_sel_hi:[1,0]
	v_pk_mul_f32 v[220:221], v[216:217], v[226:227] op_sel_hi:[1,0]
	v_pk_mul_f32 v[222:223], v[214:215], v[228:229] op_sel_hi:[1,0]
	v_pk_mul_f32 v[224:225], v[216:217], v[228:229] op_sel_hi:[1,0]
	v_pk_fma_f32 v[218:219], v[214:215], v[218:219], 1.0 op_sel_hi:[1,1,0]
	v_pk_fma_f32 v[220:221], v[216:217], v[220:221], 1.0 op_sel_hi:[1,1,0]
	v_pk_mul_f32 v[222:223], v[222:223], v[218:219] neg_lo:[0,1] neg_hi:[0,1]
	v_pk_mul_f32 v[224:225], v[224:225], v[220:221] neg_lo:[0,1] neg_hi:[0,1]
	v_pk_mul_f32 v[222:223], v[222:223], v[230:231] op_sel_hi:[1,0]
	v_pk_mul_f32 v[224:225], v[224:225], v[230:231] op_sel_hi:[1,0]
	v_exp_f32_e32 v222, v222
	v_exp_f32_e32 v223, v223
	v_exp_f32_e32 v224, v224
	v_exp_f32_e32 v225, v225
	v_pk_add_f32 v[222:223], v[222:223], 1.0 op_sel_hi:[1,0]
	v_pk_add_f32 v[224:225], v[224:225], 1.0 op_sel_hi:[1,0]
	v_rcp_f32_e32 v222, v222
	v_rcp_f32_e32 v223, v223
	v_rcp_f32_e32 v224, v224
	v_rcp_f32_e32 v225, v225
	v_pk_mul_f32 v[218:219], v[214:215], v[222:223]
	v_pk_mul_f32 v[220:221], v[216:217], v[224:225]
	v_pk_mul_f32 v[126:127], v[126:127], v[218:219]
	v_pk_mul_f32 v[128:129], v[128:129], v[220:221]
	v_pk_fma_f32 v[214:215], v[70:71], v[114:115], v[78:79]
	v_pk_fma_f32 v[216:217], v[72:73], v[116:117], v[80:81]
	v_fmac_f32_dpp v214, v114, v54 row_shr:1 row_mask:0xf bank_mask:0xf
	v_fmac_f32_dpp v215, v115, v55 row_shr:1 row_mask:0xf bank_mask:0xf
	v_fmac_f32_dpp v216, v116, v56 row_shr:1 row_mask:0xf bank_mask:0xf
	v_fmac_f32_dpp v217, v117, v57 row_shr:1 row_mask:0xf bank_mask:0xf
	v_fmac_f32_dpp v214, v130, v54 row_shl:15 row_mask:0xf bank_mask:0xf
	v_fmac_f32_dpp v215, v131, v55 row_shl:15 row_mask:0xf bank_mask:0xf
	v_fmac_f32_dpp v216, v132, v56 row_shl:15 row_mask:0xf bank_mask:0xf
	v_fmac_f32_dpp v217, v133, v57 row_shl:15 row_mask:0xf bank_mask:0xf
	v_fmac_f32_dpp v214, v114, v46 row_shr:2 row_mask:0xf bank_mask:0xf
	v_fmac_f32_dpp v215, v115, v47 row_shr:2 row_mask:0xf bank_mask:0xf
	v_fmac_f32_dpp v216, v116, v48 row_shr:2 row_mask:0xf bank_mask:0xf
	v_fmac_f32_dpp v217, v117, v49 row_shr:2 row_mask:0xf bank_mask:0xf
	v_fmac_f32_dpp v214, v130, v46 row_shl:14 row_mask:0xf bank_mask:0xf
	v_fmac_f32_dpp v215, v131, v47 row_shl:14 row_mask:0xf bank_mask:0xf
	v_fmac_f32_dpp v216, v132, v48 row_shl:14 row_mask:0xf bank_mask:0xf
	v_fmac_f32_dpp v217, v133, v49 row_shl:14 row_mask:0xf bank_mask:0xf
	v_pk_mul_f32 v[218:219], v[214:215], v[226:227] op_sel_hi:[1,0]
	v_pk_mul_f32 v[220:221], v[216:217], v[226:227] op_sel_hi:[1,0]
	v_pk_mul_f32 v[222:223], v[214:215], v[228:229] op_sel_hi:[1,0]
	v_pk_mul_f32 v[224:225], v[216:217], v[228:229] op_sel_hi:[1,0]
	v_pk_fma_f32 v[218:219], v[214:215], v[218:219], 1.0 op_sel_hi:[1,1,0]
	v_pk_fma_f32 v[220:221], v[216:217], v[220:221], 1.0 op_sel_hi:[1,1,0]
	v_pk_mul_f32 v[222:223], v[222:223], v[218:219] neg_lo:[0,1] neg_hi:[0,1]
	v_pk_mul_f32 v[224:225], v[224:225], v[220:221] neg_lo:[0,1] neg_hi:[0,1]
	v_pk_mul_f32 v[222:223], v[222:223], v[230:231] op_sel_hi:[1,0]
	v_pk_mul_f32 v[224:225], v[224:225], v[230:231] op_sel_hi:[1,0]
	v_exp_f32_e32 v222, v222
	v_exp_f32_e32 v223, v223
	v_exp_f32_e32 v224, v224
	v_exp_f32_e32 v225, v225
	v_pk_add_f32 v[222:223], v[222:223], 1.0 op_sel_hi:[1,0]
	v_pk_add_f32 v[224:225], v[224:225], 1.0 op_sel_hi:[1,0]
	v_rcp_f32_e32 v222, v222
	v_rcp_f32_e32 v223, v223
	v_rcp_f32_e32 v224, v224
	v_rcp_f32_e32 v225, v225
	v_pk_mul_f32 v[218:219], v[214:215], v[222:223]
	v_pk_mul_f32 v[220:221], v[216:217], v[224:225]
	v_pk_mul_f32 v[122:123], v[122:123], v[218:219]
	v_pk_mul_f32 v[124:125], v[124:125], v[220:221]
	v_cvt_pk_bf16_f32 v126, v126, v127
	v_cvt_pk_bf16_f32 v127, v128, v129
	v_cvt_pk_bf16_f32 v128, v122, v123
	v_cvt_pk_bf16_f32 v129, v124, v125
	v_add_u32_e32 v222, 0x80000, v195
	global_store_dwordx4 v222, v[126:129], s[70:71]
	v_pk_fma_f32 v[214:215], v[66:67], v[102:103], v[74:75]
	v_pk_fma_f32 v[216:217], v[68:69], v[104:105], v[76:77]
	v_fmac_f32_dpp v214, v102, v50 row_shr:1 row_mask:0xf bank_mask:0xf
	v_fmac_f32_dpp v215, v103, v51 row_shr:1 row_mask:0xf bank_mask:0xf
	v_fmac_f32_dpp v216, v104, v52 row_shr:1 row_mask:0xf bank_mask:0xf
	v_fmac_f32_dpp v217, v105, v53 row_shr:1 row_mask:0xf bank_mask:0xf
	v_fmac_f32_dpp v214, v118, v50 row_shl:15 row_mask:0xf bank_mask:0xf
	v_fmac_f32_dpp v215, v119, v51 row_shl:15 row_mask:0xf bank_mask:0xf
	v_fmac_f32_dpp v216, v120, v52 row_shl:15 row_mask:0xf bank_mask:0xf
	v_fmac_f32_dpp v217, v121, v53 row_shl:15 row_mask:0xf bank_mask:0xf
	v_fmac_f32_dpp v214, v102, v42 row_shr:2 row_mask:0xf bank_mask:0xf
	v_fmac_f32_dpp v215, v103, v43 row_shr:2 row_mask:0xf bank_mask:0xf
	v_fmac_f32_dpp v216, v104, v44 row_shr:2 row_mask:0xf bank_mask:0xf
	v_fmac_f32_dpp v217, v105, v45 row_shr:2 row_mask:0xf bank_mask:0xf
	v_fmac_f32_dpp v214, v118, v42 row_shl:14 row_mask:0xf bank_mask:0xf
	v_fmac_f32_dpp v215, v119, v43 row_shl:14 row_mask:0xf bank_mask:0xf
	v_fmac_f32_dpp v216, v120, v44 row_shl:14 row_mask:0xf bank_mask:0xf
	v_fmac_f32_dpp v217, v121, v45 row_shl:14 row_mask:0xf bank_mask:0xf
	v_pk_mul_f32 v[218:219], v[214:215], v[226:227] op_sel_hi:[1,0]
	v_pk_mul_f32 v[220:221], v[216:217], v[226:227] op_sel_hi:[1,0]
	v_pk_mul_f32 v[222:223], v[214:215], v[228:229] op_sel_hi:[1,0]
	v_pk_mul_f32 v[224:225], v[216:217], v[228:229] op_sel_hi:[1,0]
	v_pk_fma_f32 v[218:219], v[214:215], v[218:219], 1.0 op_sel_hi:[1,1,0]
	v_pk_fma_f32 v[220:221], v[216:217], v[220:221], 1.0 op_sel_hi:[1,1,0]
; __device__ __forceinline__ u32x4 pack8(const f32x4 a, const f32x4 b) { u32x4 w; w.x = cvt_pk_bf16(a[0], a[1]); w.y = cvt_pk_bf16(a[2], a[3]); w.z = cvt_pk_bf16(b[0], b[1]); w.w = cvt_pk_bf16(b[2], b[3]); return w; }
; template <int CTRL> __device__ __forceinline__ float dppf(float v) { return __builtin_bit_cast(float, __builtin_amdgcn_update_dpp(0, __builtin_bit_cast(int, v), CTRL, 0xf, 0xf, true)); }
; #define PG8_LAS __attribute__((address_space(3)))
; __device__ __forceinline__ float gelu_tanh(float x) {
;     const float u2 = 1.5957691216057308f * x * (1.0f + 0.044715f * x * x);
;     return x * __builtin_amdgcn_rcpf(1.0f + __builtin_amdgcn_exp2f(-u2 * LOG2E));
; }
;     __device__ __forceinline__ void operator()(const f32x4 (&acc)[2][2][4][2], const Unit& u, int wr, int wc, int fr, int fq) const {
;     ...
;                 } else if (m == 0) {
;                     if (blk > 0) {
; #pragma unroll
;                         for (int n = 0; n < 2; ++n) { const f32x4 c14 = *(const PG8_LAS f32x4*)(xbuf + ((blk - 1) * 2 + 0) * 128 + cl + 4 * n), c15 = *(const PG8_LAS f32x4*)(xbuf + ((blk - 1) * 2 + 1) * 128 + cl + 4 * n);
;                             w1[n] = c15; w2[n] = fr == 0 ? c14 : c15; }
;                     } else { w1[0] = w1[1] = w2[0] = w2[1] = (f32x4){0.f, 0.f, 0.f, 0.f}; }
;                 } else {
; #pragma unroll
;                     for (int n = 0; n < 2; ++n)
; #pragma unroll
;                         for (int i = 0; i < 4; ++i) { const float ap = acc[ai][0][m - 1][n][i]; w1[n][i] = dppf<0x10F>(ap); w2[n][i] = dppf<0x10E>(ap); }
;                 }
;                 f32x4 hv[2];
; #pragma unroll
;                 for (int n = 0; n < 2; ++n) {
;                     const f32x4 a = acc[ai][0][m][n], b = acc[ai][1][m][n];
; #pragma unroll
;                     for (int i = 0; i < 4; ++i) {
;                         const float s1 = dppf<0x111>(a[i]), s2 = dppf<0x112>(a[i]);
;                         const float p1 = fr >= 1 ? s1 : w1[n][i], p2 = fr >= 2 ? s2 : w2[n][i];
;                         const float ac = cw0[n][i] * p2 + cw1[n][i] * p1 + cw2[n][i] * a[i] + cb[n][i];
;                         hv[n][i] = gelu_tanh(ac) * b[i];
;                     }
;                 }
;                 *(u32x4*)(hh + (size_t)row * DFF + cgc) = pack8(hv[0], hv[1]);
	v_pk_mul_f32 v[222:223], v[222:223], v[218:219] neg_lo:[0,1] neg_hi:[0,1]
	v_pk_mul_f32 v[224:225], v[224:225], v[220:221] neg_lo:[0,1] neg_hi:[0,1]
	v_pk_mul_f32 v[222:223], v[222:223], v[230:231] op_sel_hi:[1,0]
	v_pk_mul_f32 v[224:225], v[224:225], v[230:231] op_sel_hi:[1,0]
	v_exp_f32_e32 v222, v222
	v_exp_f32_e32 v223, v223
	v_exp_f32_e32 v224, v224
	v_exp_f32_e32 v225, v225
	v_pk_add_f32 v[222:223], v[222:223], 1.0 op_sel_hi:[1,0]
	v_pk_add_f32 v[224:225], v[224:225], 1.0 op_sel_hi:[1,0]
	v_rcp_f32_e32 v222, v222
	v_rcp_f32_e32 v223, v223
	v_rcp_f32_e32 v224, v224
	v_rcp_f32_e32 v225, v225
	v_pk_mul_f32 v[218:219], v[214:215], v[222:223]
	v_pk_mul_f32 v[220:221], v[216:217], v[224:225]
	v_pk_mul_f32 v[110:111], v[110:111], v[218:219]
	v_pk_mul_f32 v[112:113], v[112:113], v[220:221]
	v_pk_fma_f32 v[214:215], v[70:71], v[98:99], v[78:79]
	v_pk_fma_f32 v[216:217], v[72:73], v[100:101], v[80:81]
	v_fmac_f32_dpp v214, v98, v54 row_shr:1 row_mask:0xf bank_mask:0xf
	v_fmac_f32_dpp v215, v99, v55 row_shr:1 row_mask:0xf bank_mask:0xf
	v_fmac_f32_dpp v216, v100, v56 row_shr:1 row_mask:0xf bank_mask:0xf
	v_fmac_f32_dpp v217, v101, v57 row_shr:1 row_mask:0xf bank_mask:0xf
	v_fmac_f32_dpp v214, v114, v54 row_shl:15 row_mask:0xf bank_mask:0xf
	v_fmac_f32_dpp v215, v115, v55 row_shl:15 row_mask:0xf bank_mask:0xf
	v_fmac_f32_dpp v216, v116, v56 row_shl:15 row_mask:0xf bank_mask:0xf
	v_fmac_f32_dpp v217, v117, v57 row_shl:15 row_mask:0xf bank_mask:0xf
	v_fmac_f32_dpp v214, v98, v46 row_shr:2 row_mask:0xf bank_mask:0xf
	v_fmac_f32_dpp v215, v99, v47 row_shr:2 row_mask:0xf bank_mask:0xf
	v_fmac_f32_dpp v216, v100, v48 row_shr:2 row_mask:0xf bank_mask:0xf
	v_fmac_f32_dpp v217, v101, v49 row_shr:2 row_mask:0xf bank_mask:0xf
	v_fmac_f32_dpp v214, v114, v46 row_shl:14 row_mask:0xf bank_mask:0xf
	v_fmac_f32_dpp v215, v115, v47 row_shl:14 row_mask:0xf bank_mask:0xf
	v_fmac_f32_dpp v216, v116, v48 row_shl:14 row_mask:0xf bank_mask:0xf
	v_fmac_f32_dpp v217, v117, v49 row_shl:14 row_mask:0xf bank_mask:0xf
	v_pk_mul_f32 v[218:219], v[214:215], v[226:227] op_sel_hi:[1,0]
	v_pk_mul_f32 v[220:221], v[216:217], v[226:227] op_sel_hi:[1,0]
	v_pk_mul_f32 v[222:223], v[214:215], v[228:229] op_sel_hi:[1,0]
	v_pk_mul_f32 v[224:225], v[216:217], v[228:229] op_sel_hi:[1,0]
	v_pk_fma_f32 v[218:219], v[214:215], v[218:219], 1.0 op_sel_hi:[1,1,0]
	v_pk_fma_f32 v[220:221], v[216:217], v[220:221], 1.0 op_sel_hi:[1,1,0]
	v_pk_mul_f32 v[222:223], v[222:223], v[218:219] neg_lo:[0,1] neg_hi:[0,1]
	v_pk_mul_f32 v[224:225], v[224:225], v[220:221] neg_lo:[0,1] neg_hi:[0,1]
	v_pk_mul_f32 v[222:223], v[222:223], v[230:231] op_sel_hi:[1,0]
	v_pk_mul_f32 v[224:225], v[224:225], v[230:231] op_sel_hi:[1,0]
	v_exp_f32_e32 v222, v222
	v_exp_f32_e32 v223, v223
	v_exp_f32_e32 v224, v224
	v_exp_f32_e32 v225, v225
	v_pk_add_f32 v[222:223], v[222:223], 1.0 op_sel_hi:[1,0]
	v_pk_add_f32 v[224:225], v[224:225], 1.0 op_sel_hi:[1,0]
	v_rcp_f32_e32 v222, v222
	v_rcp_f32_e32 v223, v223
	v_rcp_f32_e32 v224, v224
	v_rcp_f32_e32 v225, v225
	v_pk_mul_f32 v[218:219], v[214:215], v[222:223]
	v_pk_mul_f32 v[220:221], v[216:217], v[224:225]
	v_pk_mul_f32 v[106:107], v[106:107], v[218:219]
	v_pk_mul_f32 v[108:109], v[108:109], v[220:221]
	v_cvt_pk_bf16_f32 v110, v110, v111
	v_cvt_pk_bf16_f32 v111, v112, v113
	v_cvt_pk_bf16_f32 v112, v106, v107
	v_cvt_pk_bf16_f32 v113, v108, v109
	v_add_u32_e32 v222, 0xc0000, v195
	global_store_dwordx4 v222, v[110:113], s[70:71]
	ds_read_b128 v[162:165], v197 offset:1024
	ds_read_b128 v[166:169], v197 offset:1040
	s_waitcnt lgkmcnt(0)
	v_pk_fma_f32 v[214:215], v[66:67], v[86:87], v[74:75]
	v_pk_fma_f32 v[216:217], v[68:69], v[88:89], v[76:77]
	v_fmac_f32_dpp v214, v86, v50 row_shr:1 row_mask:0xf bank_mask:0xf
	v_fmac_f32_dpp v215, v87, v51 row_shr:1 row_mask:0xf bank_mask:0xf
	v_fmac_f32_dpp v216, v88, v52 row_shr:1 row_mask:0xf bank_mask:0xf
	v_fmac_f32_dpp v217, v89, v53 row_shr:1 row_mask:0xf bank_mask:0xf
	v_fmac_f32_dpp v214, v162, v50 row_shl:15 row_mask:0xf bank_mask:0xf
	v_fmac_f32_dpp v215, v163, v51 row_shl:15 row_mask:0xf bank_mask:0xf
	v_fmac_f32_dpp v216, v164, v52 row_shl:15 row_mask:0xf bank_mask:0xf
	v_fmac_f32_dpp v217, v165, v53 row_shl:15 row_mask:0xf bank_mask:0xf
	v_fmac_f32_dpp v214, v86, v42 row_shr:2 row_mask:0xf bank_mask:0xf
	v_fmac_f32_dpp v215, v87, v43 row_shr:2 row_mask:0xf bank_mask:0xf
	v_fmac_f32_dpp v216, v88, v44 row_shr:2 row_mask:0xf bank_mask:0xf
	v_fmac_f32_dpp v217, v89, v45 row_shr:2 row_mask:0xf bank_mask:0xf
	v_fmac_f32_dpp v214, v162, v42 row_shl:14 row_mask:0xf bank_mask:0xf
	v_fmac_f32_dpp v215, v163, v43 row_shl:14 row_mask:0xf bank_mask:0xf
	v_fmac_f32_dpp v216, v164, v44 row_shl:14 row_mask:0xf bank_mask:0xf
	v_fmac_f32_dpp v217, v165, v45 row_shl:14 row_mask:0xf bank_mask:0xf
	v_pk_mul_f32 v[218:219], v[214:215], v[226:227] op_sel_hi:[1,0]
	v_pk_mul_f32 v[220:221], v[216:217], v[226:227] op_sel_hi:[1,0]
	v_pk_mul_f32 v[222:223], v[214:215], v[228:229] op_sel_hi:[1,0]
	v_pk_mul_f32 v[224:225], v[216:217], v[228:229] op_sel_hi:[1,0]
	v_pk_fma_f32 v[218:219], v[214:215], v[218:219], 1.0 op_sel_hi:[1,1,0]
	v_pk_fma_f32 v[220:221], v[216:217], v[220:221], 1.0 op_sel_hi:[1,1,0]
	v_pk_mul_f32 v[222:223], v[222:223], v[218:219] neg_lo:[0,1] neg_hi:[0,1]
	v_pk_mul_f32 v[224:225], v[224:225], v[220:221] neg_lo:[0,1] neg_hi:[0,1]
	v_pk_mul_f32 v[222:223], v[222:223], v[230:231] op_sel_hi:[1,0]
	v_pk_mul_f32 v[224:225], v[224:225], v[230:231] op_sel_hi:[1,0]
	v_exp_f32_e32 v222, v222
	v_exp_f32_e32 v223, v223
	v_exp_f32_e32 v224, v224
	v_exp_f32_e32 v225, v225
	v_pk_add_f32 v[222:223], v[222:223], 1.0 op_sel_hi:[1,0]
; __device__ __forceinline__ u32x4 pack8(const f32x4 a, const f32x4 b) { u32x4 w; w.x = cvt_pk_bf16(a[0], a[1]); w.y = cvt_pk_bf16(a[2], a[3]); w.z = cvt_pk_bf16(b[0], b[1]); w.w = cvt_pk_bf16(b[2], b[3]); return w; }
; template <int CTRL> __device__ __forceinline__ float dppf(float v) { return __builtin_bit_cast(float, __builtin_amdgcn_update_dpp(0, __builtin_bit_cast(int, v), CTRL, 0xf, 0xf, true)); }
; __device__ __forceinline__ float gelu_tanh(float x) {
;     const float u2 = 1.5957691216057308f * x * (1.0f + 0.044715f * x * x);
;     return x * __builtin_amdgcn_rcpf(1.0f + __builtin_amdgcn_exp2f(-u2 * LOG2E));
; }
;     __device__ __forceinline__ void operator()(const f32x4 (&acc)[2][2][4][2], const Unit& u, int wr, int wc, int fr, int fq) const {
;     ...
;                 f32x4 hv[2];
; #pragma unroll
;                 for (int n = 0; n < 2; ++n) {
;                     const f32x4 a = acc[ai][0][m][n], b = acc[ai][1][m][n];
; #pragma unroll
;                     for (int i = 0; i < 4; ++i) {
;                         const float s1 = dppf<0x111>(a[i]), s2 = dppf<0x112>(a[i]);
;                         const float p1 = fr >= 1 ? s1 : w1[n][i], p2 = fr >= 2 ? s2 : w2[n][i];
;                         const float ac = cw0[n][i] * p2 + cw1[n][i] * p1 + cw2[n][i] * a[i] + cb[n][i];
;                         hv[n][i] = gelu_tanh(ac) * b[i];
;                     }
;                 }
;                 *(u32x4*)(hh + (size_t)row * DFF + cgc) = pack8(hv[0], hv[1]);
	v_pk_add_f32 v[224:225], v[224:225], 1.0 op_sel_hi:[1,0]
	v_rcp_f32_e32 v222, v222
	v_rcp_f32_e32 v223, v223
	v_rcp_f32_e32 v224, v224
	v_rcp_f32_e32 v225, v225
	v_pk_mul_f32 v[218:219], v[214:215], v[222:223]
	v_pk_mul_f32 v[220:221], v[216:217], v[224:225]
	v_pk_mul_f32 v[94:95], v[94:95], v[218:219]
	v_pk_mul_f32 v[96:97], v[96:97], v[220:221]
	v_pk_fma_f32 v[214:215], v[70:71], v[82:83], v[78:79]
	v_pk_fma_f32 v[216:217], v[72:73], v[84:85], v[80:81]
	v_fmac_f32_dpp v214, v82, v54 row_shr:1 row_mask:0xf bank_mask:0xf
	v_fmac_f32_dpp v215, v83, v55 row_shr:1 row_mask:0xf bank_mask:0xf
	v_fmac_f32_dpp v216, v84, v56 row_shr:1 row_mask:0xf bank_mask:0xf
	v_fmac_f32_dpp v217, v85, v57 row_shr:1 row_mask:0xf bank_mask:0xf
	v_fmac_f32_dpp v214, v166, v54 row_shl:15 row_mask:0xf bank_mask:0xf
	v_fmac_f32_dpp v215, v167, v55 row_shl:15 row_mask:0xf bank_mask:0xf
	v_fmac_f32_dpp v216, v168, v56 row_shl:15 row_mask:0xf bank_mask:0xf
	v_fmac_f32_dpp v217, v169, v57 row_shl:15 row_mask:0xf bank_mask:0xf
	v_fmac_f32_dpp v214, v82, v46 row_shr:2 row_mask:0xf bank_mask:0xf
	v_fmac_f32_dpp v215, v83, v47 row_shr:2 row_mask:0xf bank_mask:0xf
	v_fmac_f32_dpp v216, v84, v48 row_shr:2 row_mask:0xf bank_mask:0xf
	v_fmac_f32_dpp v217, v85, v49 row_shr:2 row_mask:0xf bank_mask:0xf
	v_fmac_f32_dpp v214, v166, v46 row_shl:14 row_mask:0xf bank_mask:0xf
	v_fmac_f32_dpp v215, v167, v47 row_shl:14 row_mask:0xf bank_mask:0xf
	v_fmac_f32_dpp v216, v168, v48 row_shl:14 row_mask:0xf bank_mask:0xf
	v_fmac_f32_dpp v217, v169, v49 row_shl:14 row_mask:0xf bank_mask:0xf
	v_pk_mul_f32 v[218:219], v[214:215], v[226:227] op_sel_hi:[1,0]
	v_pk_mul_f32 v[220:221], v[216:217], v[226:227] op_sel_hi:[1,0]
	v_pk_mul_f32 v[222:223], v[214:215], v[228:229] op_sel_hi:[1,0]
	v_pk_mul_f32 v[224:225], v[216:217], v[228:229] op_sel_hi:[1,0]
	v_pk_fma_f32 v[218:219], v[214:215], v[218:219], 1.0 op_sel_hi:[1,1,0]
	v_pk_fma_f32 v[220:221], v[216:217], v[220:221], 1.0 op_sel_hi:[1,1,0]
	v_pk_mul_f32 v[222:223], v[222:223], v[218:219] neg_lo:[0,1] neg_hi:[0,1]
	v_pk_mul_f32 v[224:225], v[224:225], v[220:221] neg_lo:[0,1] neg_hi:[0,1]
	v_pk_mul_f32 v[222:223], v[222:223], v[230:231] op_sel_hi:[1,0]
	v_pk_mul_f32 v[224:225], v[224:225], v[230:231] op_sel_hi:[1,0]
	v_exp_f32_e32 v222, v222
	v_exp_f32_e32 v223, v223
	v_exp_f32_e32 v224, v224
	v_exp_f32_e32 v225, v225
	v_pk_add_f32 v[222:223], v[222:223], 1.0 op_sel_hi:[1,0]
	v_pk_add_f32 v[224:225], v[224:225], 1.0 op_sel_hi:[1,0]
	v_rcp_f32_e32 v222, v222
	v_rcp_f32_e32 v223, v223
	v_rcp_f32_e32 v224, v224
	v_rcp_f32_e32 v225, v225
	v_pk_mul_f32 v[218:219], v[214:215], v[222:223]
	v_pk_mul_f32 v[220:221], v[216:217], v[224:225]
	v_pk_mul_f32 v[90:91], v[90:91], v[218:219]
	v_pk_mul_f32 v[92:93], v[92:93], v[220:221]
	v_cvt_pk_bf16_f32 v94, v94, v95
	v_cvt_pk_bf16_f32 v95, v96, v97
	v_cvt_pk_bf16_f32 v96, v90, v91
	v_cvt_pk_bf16_f32 v97, v92, v93
	v_add_u32_e32 v222, 0x200000, v195
	global_store_dwordx4 v222, v[94:97], s[70:71]
	v_pk_fma_f32 v[214:215], v[66:67], v[38:39], v[74:75]
	v_pk_fma_f32 v[216:217], v[68:69], v[40:41], v[76:77]
	v_fmac_f32_dpp v214, v38, v50 row_shr:1 row_mask:0xf bank_mask:0xf
	v_fmac_f32_dpp v215, v39, v51 row_shr:1 row_mask:0xf bank_mask:0xf
	v_fmac_f32_dpp v216, v40, v52 row_shr:1 row_mask:0xf bank_mask:0xf
	v_fmac_f32_dpp v217, v41, v53 row_shr:1 row_mask:0xf bank_mask:0xf
	v_fmac_f32_dpp v214, v86, v50 row_shl:15 row_mask:0xf bank_mask:0xf
	v_fmac_f32_dpp v215, v87, v51 row_shl:15 row_mask:0xf bank_mask:0xf
	v_fmac_f32_dpp v216, v88, v52 row_shl:15 row_mask:0xf bank_mask:0xf
	v_fmac_f32_dpp v217, v89, v53 row_shl:15 row_mask:0xf bank_mask:0xf
	v_fmac_f32_dpp v214, v38, v42 row_shr:2 row_mask:0xf bank_mask:0xf
	v_fmac_f32_dpp v215, v39, v43 row_shr:2 row_mask:0xf bank_mask:0xf
	v_fmac_f32_dpp v216, v40, v44 row_shr:2 row_mask:0xf bank_mask:0xf
	v_fmac_f32_dpp v217, v41, v45 row_shr:2 row_mask:0xf bank_mask:0xf
	v_fmac_f32_dpp v214, v86, v42 row_shl:14 row_mask:0xf bank_mask:0xf
	v_fmac_f32_dpp v215, v87, v43 row_shl:14 row_mask:0xf bank_mask:0xf
	v_fmac_f32_dpp v216, v88, v44 row_shl:14 row_mask:0xf bank_mask:0xf
	v_fmac_f32_dpp v217, v89, v45 row_shl:14 row_mask:0xf bank_mask:0xf
	v_pk_mul_f32 v[218:219], v[214:215], v[226:227] op_sel_hi:[1,0]
	v_pk_mul_f32 v[220:221], v[216:217], v[226:227] op_sel_hi:[1,0]
	v_pk_mul_f32 v[222:223], v[214:215], v[228:229] op_sel_hi:[1,0]
	v_pk_mul_f32 v[224:225], v[216:217], v[228:229] op_sel_hi:[1,0]
	v_pk_fma_f32 v[218:219], v[214:215], v[218:219], 1.0 op_sel_hi:[1,1,0]
	v_pk_fma_f32 v[220:221], v[216:217], v[220:221], 1.0 op_sel_hi:[1,1,0]
	v_pk_mul_f32 v[222:223], v[222:223], v[218:219] neg_lo:[0,1] neg_hi:[0,1]
	v_pk_mul_f32 v[224:225], v[224:225], v[220:221] neg_lo:[0,1] neg_hi:[0,1]
	v_pk_mul_f32 v[222:223], v[222:223], v[230:231] op_sel_hi:[1,0]
	v_pk_mul_f32 v[224:225], v[224:225], v[230:231] op_sel_hi:[1,0]
	v_exp_f32_e32 v222, v222
	v_exp_f32_e32 v223, v223
	v_exp_f32_e32 v224, v224
	v_exp_f32_e32 v225, v225
	v_pk_add_f32 v[222:223], v[222:223], 1.0 op_sel_hi:[1,0]
	v_pk_add_f32 v[224:225], v[224:225], 1.0 op_sel_hi:[1,0]
	v_rcp_f32_e32 v222, v222
	v_rcp_f32_e32 v223, v223
	v_rcp_f32_e32 v224, v224
	v_rcp_f32_e32 v225, v225
	v_pk_mul_f32 v[218:219], v[214:215], v[222:223]
	v_pk_mul_f32 v[220:221], v[216:217], v[224:225]
	v_pk_mul_f32 v[62:63], v[62:63], v[218:219]
	v_pk_mul_f32 v[64:65], v[64:65], v[220:221]
	v_pk_fma_f32 v[214:215], v[70:71], v[34:35], v[78:79]
	v_pk_fma_f32 v[216:217], v[72:73], v[36:37], v[80:81]
	v_fmac_f32_dpp v214, v34, v54 row_shr:1 row_mask:0xf bank_mask:0xf
	v_fmac_f32_dpp v215, v35, v55 row_shr:1 row_mask:0xf bank_mask:0xf
; __device__ __forceinline__ u32x4 pack8(const f32x4 a, const f32x4 b) { u32x4 w; w.x = cvt_pk_bf16(a[0], a[1]); w.y = cvt_pk_bf16(a[2], a[3]); w.z = cvt_pk_bf16(b[0], b[1]); w.w = cvt_pk_bf16(b[2], b[3]); return w; }
; template <int CTRL> __device__ __forceinline__ float dppf(float v) { return __builtin_bit_cast(float, __builtin_amdgcn_update_dpp(0, __builtin_bit_cast(int, v), CTRL, 0xf, 0xf, true)); }
; __device__ __forceinline__ float gelu_tanh(float x) {
;     const float u2 = 1.5957691216057308f * x * (1.0f + 0.044715f * x * x);
;     return x * __builtin_amdgcn_rcpf(1.0f + __builtin_amdgcn_exp2f(-u2 * LOG2E));
; }
;     __device__ __forceinline__ void operator()(const f32x4 (&acc)[2][2][4][2], const Unit& u, int wr, int wc, int fr, int fq) const {
;     ...
;                 f32x4 hv[2];
; #pragma unroll
;                 for (int n = 0; n < 2; ++n) {
;                     const f32x4 a = acc[ai][0][m][n], b = acc[ai][1][m][n];
; #pragma unroll
;                     for (int i = 0; i < 4; ++i) {
;                         const float s1 = dppf<0x111>(a[i]), s2 = dppf<0x112>(a[i]);
;                         const float p1 = fr >= 1 ? s1 : w1[n][i], p2 = fr >= 2 ? s2 : w2[n][i];
;                         const float ac = cw0[n][i] * p2 + cw1[n][i] * p1 + cw2[n][i] * a[i] + cb[n][i];
;                         hv[n][i] = gelu_tanh(ac) * b[i];
;                     }
;                 }
;                 *(u32x4*)(hh + (size_t)row * DFF + cgc) = pack8(hv[0], hv[1]);
	v_fmac_f32_dpp v216, v36, v56 row_shr:1 row_mask:0xf bank_mask:0xf
	v_fmac_f32_dpp v217, v37, v57 row_shr:1 row_mask:0xf bank_mask:0xf
	v_fmac_f32_dpp v214, v82, v54 row_shl:15 row_mask:0xf bank_mask:0xf
	v_fmac_f32_dpp v215, v83, v55 row_shl:15 row_mask:0xf bank_mask:0xf
	v_fmac_f32_dpp v216, v84, v56 row_shl:15 row_mask:0xf bank_mask:0xf
	v_fmac_f32_dpp v217, v85, v57 row_shl:15 row_mask:0xf bank_mask:0xf
	v_fmac_f32_dpp v214, v34, v46 row_shr:2 row_mask:0xf bank_mask:0xf
	v_fmac_f32_dpp v215, v35, v47 row_shr:2 row_mask:0xf bank_mask:0xf
	v_fmac_f32_dpp v216, v36, v48 row_shr:2 row_mask:0xf bank_mask:0xf
	v_fmac_f32_dpp v217, v37, v49 row_shr:2 row_mask:0xf bank_mask:0xf
	v_fmac_f32_dpp v214, v82, v46 row_shl:14 row_mask:0xf bank_mask:0xf
	v_fmac_f32_dpp v215, v83, v47 row_shl:14 row_mask:0xf bank_mask:0xf
	v_fmac_f32_dpp v216, v84, v48 row_shl:14 row_mask:0xf bank_mask:0xf
	v_fmac_f32_dpp v217, v85, v49 row_shl:14 row_mask:0xf bank_mask:0xf
	v_pk_mul_f32 v[218:219], v[214:215], v[226:227] op_sel_hi:[1,0]
	v_pk_mul_f32 v[220:221], v[216:217], v[226:227] op_sel_hi:[1,0]
	v_pk_mul_f32 v[222:223], v[214:215], v[228:229] op_sel_hi:[1,0]
	v_pk_mul_f32 v[224:225], v[216:217], v[228:229] op_sel_hi:[1,0]
	v_pk_fma_f32 v[218:219], v[214:215], v[218:219], 1.0 op_sel_hi:[1,1,0]
	v_pk_fma_f32 v[220:221], v[216:217], v[220:221], 1.0 op_sel_hi:[1,1,0]
	v_pk_mul_f32 v[222:223], v[222:223], v[218:219] neg_lo:[0,1] neg_hi:[0,1]
	v_pk_mul_f32 v[224:225], v[224:225], v[220:221] neg_lo:[0,1] neg_hi:[0,1]
	v_pk_mul_f32 v[222:223], v[222:223], v[230:231] op_sel_hi:[1,0]
	v_pk_mul_f32 v[224:225], v[224:225], v[230:231] op_sel_hi:[1,0]
	v_exp_f32_e32 v222, v222
	v_exp_f32_e32 v223, v223
	v_exp_f32_e32 v224, v224
	v_exp_f32_e32 v225, v225
	v_pk_add_f32 v[222:223], v[222:223], 1.0 op_sel_hi:[1,0]
	v_pk_add_f32 v[224:225], v[224:225], 1.0 op_sel_hi:[1,0]
	v_rcp_f32_e32 v222, v222
	v_rcp_f32_e32 v223, v223
	v_rcp_f32_e32 v224, v224
	v_rcp_f32_e32 v225, v225
	v_pk_mul_f32 v[218:219], v[214:215], v[222:223]
	v_pk_mul_f32 v[220:221], v[216:217], v[224:225]
	v_pk_mul_f32 v[58:59], v[58:59], v[218:219]
	v_pk_mul_f32 v[60:61], v[60:61], v[220:221]
	v_cvt_pk_bf16_f32 v62, v62, v63
	v_cvt_pk_bf16_f32 v63, v64, v65
	v_cvt_pk_bf16_f32 v64, v58, v59
	v_cvt_pk_bf16_f32 v65, v60, v61
	v_add_u32_e32 v222, 0x240000, v195
	global_store_dwordx4 v222, v[62:65], s[70:71]
	v_pk_fma_f32 v[214:215], v[66:67], v[22:23], v[74:75]
	v_pk_fma_f32 v[216:217], v[68:69], v[24:25], v[76:77]
	v_fmac_f32_dpp v214, v22, v50 row_shr:1 row_mask:0xf bank_mask:0xf
	v_fmac_f32_dpp v215, v23, v51 row_shr:1 row_mask:0xf bank_mask:0xf
	v_fmac_f32_dpp v216, v24, v52 row_shr:1 row_mask:0xf bank_mask:0xf
	v_fmac_f32_dpp v217, v25, v53 row_shr:1 row_mask:0xf bank_mask:0xf
	v_fmac_f32_dpp v214, v38, v50 row_shl:15 row_mask:0xf bank_mask:0xf
	v_fmac_f32_dpp v215, v39, v51 row_shl:15 row_mask:0xf bank_mask:0xf
	v_fmac_f32_dpp v216, v40, v52 row_shl:15 row_mask:0xf bank_mask:0xf
	v_fmac_f32_dpp v217, v41, v53 row_shl:15 row_mask:0xf bank_mask:0xf
	v_fmac_f32_dpp v214, v22, v42 row_shr:2 row_mask:0xf bank_mask:0xf
	v_fmac_f32_dpp v215, v23, v43 row_shr:2 row_mask:0xf bank_mask:0xf
	v_fmac_f32_dpp v216, v24, v44 row_shr:2 row_mask:0xf bank_mask:0xf
	v_fmac_f32_dpp v217, v25, v45 row_shr:2 row_mask:0xf bank_mask:0xf
	v_fmac_f32_dpp v214, v38, v42 row_shl:14 row_mask:0xf bank_mask:0xf
	v_fmac_f32_dpp v215, v39, v43 row_shl:14 row_mask:0xf bank_mask:0xf
	v_fmac_f32_dpp v216, v40, v44 row_shl:14 row_mask:0xf bank_mask:0xf
	v_fmac_f32_dpp v217, v41, v45 row_shl:14 row_mask:0xf bank_mask:0xf
	v_pk_mul_f32 v[218:219], v[214:215], v[226:227] op_sel_hi:[1,0]
	v_pk_mul_f32 v[220:221], v[216:217], v[226:227] op_sel_hi:[1,0]
	v_pk_mul_f32 v[222:223], v[214:215], v[228:229] op_sel_hi:[1,0]
	v_pk_mul_f32 v[224:225], v[216:217], v[228:229] op_sel_hi:[1,0]
	v_pk_fma_f32 v[218:219], v[214:215], v[218:219], 1.0 op_sel_hi:[1,1,0]
	v_pk_fma_f32 v[220:221], v[216:217], v[220:221], 1.0 op_sel_hi:[1,1,0]
	v_pk_mul_f32 v[222:223], v[222:223], v[218:219] neg_lo:[0,1] neg_hi:[0,1]
	v_pk_mul_f32 v[224:225], v[224:225], v[220:221] neg_lo:[0,1] neg_hi:[0,1]
	v_pk_mul_f32 v[222:223], v[222:223], v[230:231] op_sel_hi:[1,0]
	v_pk_mul_f32 v[224:225], v[224:225], v[230:231] op_sel_hi:[1,0]
	v_exp_f32_e32 v222, v222
	v_exp_f32_e32 v223, v223
	v_exp_f32_e32 v224, v224
	v_exp_f32_e32 v225, v225
	v_pk_add_f32 v[222:223], v[222:223], 1.0 op_sel_hi:[1,0]
	v_pk_add_f32 v[224:225], v[224:225], 1.0 op_sel_hi:[1,0]
	v_rcp_f32_e32 v222, v222
	v_rcp_f32_e32 v223, v223
	v_rcp_f32_e32 v224, v224
	v_rcp_f32_e32 v225, v225
	v_pk_mul_f32 v[218:219], v[214:215], v[222:223]
	v_pk_mul_f32 v[220:221], v[216:217], v[224:225]
	v_pk_mul_f32 v[30:31], v[30:31], v[218:219]
	v_pk_mul_f32 v[32:33], v[32:33], v[220:221]
	v_pk_fma_f32 v[214:215], v[70:71], v[18:19], v[78:79]
	v_pk_fma_f32 v[216:217], v[72:73], v[20:21], v[80:81]
	v_fmac_f32_dpp v214, v18, v54 row_shr:1 row_mask:0xf bank_mask:0xf
	v_fmac_f32_dpp v215, v19, v55 row_shr:1 row_mask:0xf bank_mask:0xf
	v_fmac_f32_dpp v216, v20, v56 row_shr:1 row_mask:0xf bank_mask:0xf
	v_fmac_f32_dpp v217, v21, v57 row_shr:1 row_mask:0xf bank_mask:0xf
	v_fmac_f32_dpp v214, v34, v54 row_shl:15 row_mask:0xf bank_mask:0xf
	v_fmac_f32_dpp v215, v35, v55 row_shl:15 row_mask:0xf bank_mask:0xf
	v_fmac_f32_dpp v216, v36, v56 row_shl:15 row_mask:0xf bank_mask:0xf
	v_fmac_f32_dpp v217, v37, v57 row_shl:15 row_mask:0xf bank_mask:0xf
	v_fmac_f32_dpp v214, v18, v46 row_shr:2 row_mask:0xf bank_mask:0xf
	v_fmac_f32_dpp v215, v19, v47 row_shr:2 row_mask:0xf bank_mask:0xf
	v_fmac_f32_dpp v216, v20, v48 row_shr:2 row_mask:0xf bank_mask:0xf
; __device__ __forceinline__ u32x4 pack8(const f32x4 a, const f32x4 b) { u32x4 w; w.x = cvt_pk_bf16(a[0], a[1]); w.y = cvt_pk_bf16(a[2], a[3]); w.z = cvt_pk_bf16(b[0], b[1]); w.w = cvt_pk_bf16(b[2], b[3]); return w; }
; template <int CTRL> __device__ __forceinline__ float dppf(float v) { return __builtin_bit_cast(float, __builtin_amdgcn_update_dpp(0, __builtin_bit_cast(int, v), CTRL, 0xf, 0xf, true)); }
; __device__ __forceinline__ float gelu_tanh(float x) {
;     const float u2 = 1.5957691216057308f * x * (1.0f + 0.044715f * x * x);
;     return x * __builtin_amdgcn_rcpf(1.0f + __builtin_amdgcn_exp2f(-u2 * LOG2E));
; }
;     __device__ __forceinline__ void operator()(const f32x4 (&acc)[2][2][4][2], const Unit& u, int wr, int wc, int fr, int fq) const {
;     ...
;                 f32x4 hv[2];
; #pragma unroll
;                 for (int n = 0; n < 2; ++n) {
;                     const f32x4 a = acc[ai][0][m][n], b = acc[ai][1][m][n];
; #pragma unroll
;                     for (int i = 0; i < 4; ++i) {
;                         const float s1 = dppf<0x111>(a[i]), s2 = dppf<0x112>(a[i]);
;                         const float p1 = fr >= 1 ? s1 : w1[n][i], p2 = fr >= 2 ? s2 : w2[n][i];
;                         const float ac = cw0[n][i] * p2 + cw1[n][i] * p1 + cw2[n][i] * a[i] + cb[n][i];
;                         hv[n][i] = gelu_tanh(ac) * b[i];
;                     }
;                 }
;                 *(u32x4*)(hh + (size_t)row * DFF + cgc) = pack8(hv[0], hv[1]);
;                 if (samp) {
;                     if (fr >= 14) { const int bs = (row - MP) >> 4; float* p = out + O_CVS + ((size_t)bs * 2 + (fr - 14)) * DFF + cgc; *(f32x4*)p = acc[ai][0][m][0]; *(f32x4*)(p + 4) = acc[ai][0][m][1]; }
;                 } else {
;                     if (blk == 3 && m == 3 && fr >= 14) { float* p = tail + ((size_t)u.pm * 2 + (fr - 14)) * DFF + cgc; *(f32x4*)p = acc[ai][0][m][0]; *(f32x4*)(p + 4) = acc[ai][0][m][1];
	v_fmac_f32_dpp v217, v21, v49 row_shr:2 row_mask:0xf bank_mask:0xf
	v_fmac_f32_dpp v214, v34, v46 row_shl:14 row_mask:0xf bank_mask:0xf
	v_fmac_f32_dpp v215, v35, v47 row_shl:14 row_mask:0xf bank_mask:0xf
	v_fmac_f32_dpp v216, v36, v48 row_shl:14 row_mask:0xf bank_mask:0xf
	v_fmac_f32_dpp v217, v37, v49 row_shl:14 row_mask:0xf bank_mask:0xf
	v_pk_mul_f32 v[218:219], v[214:215], v[226:227] op_sel_hi:[1,0]
	v_pk_mul_f32 v[220:221], v[216:217], v[226:227] op_sel_hi:[1,0]
	v_pk_mul_f32 v[222:223], v[214:215], v[228:229] op_sel_hi:[1,0]
	v_pk_mul_f32 v[224:225], v[216:217], v[228:229] op_sel_hi:[1,0]
	v_pk_fma_f32 v[218:219], v[214:215], v[218:219], 1.0 op_sel_hi:[1,1,0]
	v_pk_fma_f32 v[220:221], v[216:217], v[220:221], 1.0 op_sel_hi:[1,1,0]
	v_pk_mul_f32 v[222:223], v[222:223], v[218:219] neg_lo:[0,1] neg_hi:[0,1]
	v_pk_mul_f32 v[224:225], v[224:225], v[220:221] neg_lo:[0,1] neg_hi:[0,1]
	v_pk_mul_f32 v[222:223], v[222:223], v[230:231] op_sel_hi:[1,0]
	v_pk_mul_f32 v[224:225], v[224:225], v[230:231] op_sel_hi:[1,0]
	v_exp_f32_e32 v222, v222
	v_exp_f32_e32 v223, v223
	v_exp_f32_e32 v224, v224
	v_exp_f32_e32 v225, v225
	v_pk_add_f32 v[222:223], v[222:223], 1.0 op_sel_hi:[1,0]
	v_pk_add_f32 v[224:225], v[224:225], 1.0 op_sel_hi:[1,0]
	v_rcp_f32_e32 v222, v222
	v_rcp_f32_e32 v223, v223
	v_rcp_f32_e32 v224, v224
	v_rcp_f32_e32 v225, v225
	v_pk_mul_f32 v[218:219], v[214:215], v[222:223]
	v_pk_mul_f32 v[220:221], v[216:217], v[224:225]
	v_pk_mul_f32 v[26:27], v[26:27], v[218:219]
	v_pk_mul_f32 v[28:29], v[28:29], v[220:221]
	v_cvt_pk_bf16_f32 v30, v30, v31
	v_cvt_pk_bf16_f32 v31, v32, v33
	v_cvt_pk_bf16_f32 v32, v26, v27
	v_cvt_pk_bf16_f32 v33, v28, v29
	v_add_u32_e32 v222, 0x280000, v195
	global_store_dwordx4 v222, v[30:33], s[70:71]
	v_pk_fma_f32 v[214:215], v[66:67], v[6:7], v[74:75]
	v_pk_fma_f32 v[216:217], v[68:69], v[8:9], v[76:77]
	v_fmac_f32_dpp v214, v6, v50 row_shr:1 row_mask:0xf bank_mask:0xf
	v_fmac_f32_dpp v215, v7, v51 row_shr:1 row_mask:0xf bank_mask:0xf
	v_fmac_f32_dpp v216, v8, v52 row_shr:1 row_mask:0xf bank_mask:0xf
	v_fmac_f32_dpp v217, v9, v53 row_shr:1 row_mask:0xf bank_mask:0xf
	v_fmac_f32_dpp v214, v22, v50 row_shl:15 row_mask:0xf bank_mask:0xf
	v_fmac_f32_dpp v215, v23, v51 row_shl:15 row_mask:0xf bank_mask:0xf
	v_fmac_f32_dpp v216, v24, v52 row_shl:15 row_mask:0xf bank_mask:0xf
	v_fmac_f32_dpp v217, v25, v53 row_shl:15 row_mask:0xf bank_mask:0xf
	v_fmac_f32_dpp v214, v6, v42 row_shr:2 row_mask:0xf bank_mask:0xf
	v_fmac_f32_dpp v215, v7, v43 row_shr:2 row_mask:0xf bank_mask:0xf
	v_fmac_f32_dpp v216, v8, v44 row_shr:2 row_mask:0xf bank_mask:0xf
	v_fmac_f32_dpp v217, v9, v45 row_shr:2 row_mask:0xf bank_mask:0xf
	v_fmac_f32_dpp v214, v22, v42 row_shl:14 row_mask:0xf bank_mask:0xf
	v_fmac_f32_dpp v215, v23, v43 row_shl:14 row_mask:0xf bank_mask:0xf
	v_fmac_f32_dpp v216, v24, v44 row_shl:14 row_mask:0xf bank_mask:0xf
	v_fmac_f32_dpp v217, v25, v45 row_shl:14 row_mask:0xf bank_mask:0xf
	v_pk_mul_f32 v[218:219], v[214:215], v[226:227] op_sel_hi:[1,0]
	v_pk_mul_f32 v[220:221], v[216:217], v[226:227] op_sel_hi:[1,0]
	v_pk_mul_f32 v[222:223], v[214:215], v[228:229] op_sel_hi:[1,0]
	v_pk_mul_f32 v[224:225], v[216:217], v[228:229] op_sel_hi:[1,0]
	v_pk_fma_f32 v[218:219], v[214:215], v[218:219], 1.0 op_sel_hi:[1,1,0]
	v_pk_fma_f32 v[220:221], v[216:217], v[220:221], 1.0 op_sel_hi:[1,1,0]
	v_pk_mul_f32 v[222:223], v[222:223], v[218:219] neg_lo:[0,1] neg_hi:[0,1]
	v_pk_mul_f32 v[224:225], v[224:225], v[220:221] neg_lo:[0,1] neg_hi:[0,1]
	v_pk_mul_f32 v[222:223], v[222:223], v[230:231] op_sel_hi:[1,0]
	v_pk_mul_f32 v[224:225], v[224:225], v[230:231] op_sel_hi:[1,0]
	v_exp_f32_e32 v222, v222
	v_exp_f32_e32 v223, v223
	v_exp_f32_e32 v224, v224
	v_exp_f32_e32 v225, v225
	v_pk_add_f32 v[222:223], v[222:223], 1.0 op_sel_hi:[1,0]
	v_pk_add_f32 v[224:225], v[224:225], 1.0 op_sel_hi:[1,0]
	v_rcp_f32_e32 v222, v222
	v_rcp_f32_e32 v223, v223
	v_rcp_f32_e32 v224, v224
	v_rcp_f32_e32 v225, v225
	v_pk_mul_f32 v[218:219], v[214:215], v[222:223]
	v_pk_mul_f32 v[220:221], v[216:217], v[224:225]
	v_pk_mul_f32 v[14:15], v[14:15], v[218:219]
	v_pk_mul_f32 v[16:17], v[16:17], v[220:221]
	v_pk_fma_f32 v[214:215], v[70:71], v[2:3], v[78:79]
	v_pk_fma_f32 v[216:217], v[72:73], v[4:5], v[80:81]
	v_fmac_f32_dpp v214, v2, v54 row_shr:1 row_mask:0xf bank_mask:0xf
	v_fmac_f32_dpp v215, v3, v55 row_shr:1 row_mask:0xf bank_mask:0xf
	v_fmac_f32_dpp v216, v4, v56 row_shr:1 row_mask:0xf bank_mask:0xf
	v_fmac_f32_dpp v217, v5, v57 row_shr:1 row_mask:0xf bank_mask:0xf
	v_fmac_f32_dpp v214, v18, v54 row_shl:15 row_mask:0xf bank_mask:0xf
	v_fmac_f32_dpp v215, v19, v55 row_shl:15 row_mask:0xf bank_mask:0xf
	v_fmac_f32_dpp v216, v20, v56 row_shl:15 row_mask:0xf bank_mask:0xf
	v_fmac_f32_dpp v217, v21, v57 row_shl:15 row_mask:0xf bank_mask:0xf
	v_fmac_f32_dpp v214, v2, v46 row_shr:2 row_mask:0xf bank_mask:0xf
	v_fmac_f32_dpp v215, v3, v47 row_shr:2 row_mask:0xf bank_mask:0xf
	v_fmac_f32_dpp v216, v4, v48 row_shr:2 row_mask:0xf bank_mask:0xf
	v_fmac_f32_dpp v217, v5, v49 row_shr:2 row_mask:0xf bank_mask:0xf
	v_fmac_f32_dpp v214, v18, v46 row_shl:14 row_mask:0xf bank_mask:0xf
	v_fmac_f32_dpp v215, v19, v47 row_shl:14 row_mask:0xf bank_mask:0xf
	v_fmac_f32_dpp v216, v20, v48 row_shl:14 row_mask:0xf bank_mask:0xf
	v_fmac_f32_dpp v217, v21, v49 row_shl:14 row_mask:0xf bank_mask:0xf
	v_pk_mul_f32 v[218:219], v[214:215], v[226:227] op_sel_hi:[1,0]
	v_pk_mul_f32 v[220:221], v[216:217], v[226:227] op_sel_hi:[1,0]
	v_pk_mul_f32 v[222:223], v[214:215], v[228:229] op_sel_hi:[1,0]
	v_pk_mul_f32 v[224:225], v[216:217], v[228:229] op_sel_hi:[1,0]
	v_pk_fma_f32 v[218:219], v[214:215], v[218:219], 1.0 op_sel_hi:[1,1,0]
	v_pk_fma_f32 v[220:221], v[216:217], v[220:221], 1.0 op_sel_hi:[1,1,0]
	v_pk_mul_f32 v[222:223], v[222:223], v[218:219] neg_lo:[0,1] neg_hi:[0,1]
	v_pk_mul_f32 v[224:225], v[224:225], v[220:221] neg_lo:[0,1] neg_hi:[0,1]
	v_pk_mul_f32 v[222:223], v[222:223], v[230:231] op_sel_hi:[1,0]
	v_pk_mul_f32 v[224:225], v[224:225], v[230:231] op_sel_hi:[1,0]
	v_exp_f32_e32 v222, v222
	v_exp_f32_e32 v223, v223
	v_exp_f32_e32 v224, v224
	v_exp_f32_e32 v225, v225
	v_pk_add_f32 v[222:223], v[222:223], 1.0 op_sel_hi:[1,0]
	v_pk_add_f32 v[224:225], v[224:225], 1.0 op_sel_hi:[1,0]
	v_rcp_f32_e32 v222, v222
	v_rcp_f32_e32 v223, v223
	v_rcp_f32_e32 v224, v224
	v_rcp_f32_e32 v225, v225
	v_pk_mul_f32 v[218:219], v[214:215], v[222:223]
	v_pk_mul_f32 v[220:221], v[216:217], v[224:225]
	v_pk_mul_f32 v[10:11], v[10:11], v[218:219]
	v_pk_mul_f32 v[12:13], v[12:13], v[220:221]
	v_cvt_pk_bf16_f32 v14, v14, v15
	v_cvt_pk_bf16_f32 v15, v16, v17
	v_cvt_pk_bf16_f32 v16, v10, v11
	v_cvt_pk_bf16_f32 v17, v12, v13
	v_add_u32_e32 v222, 0x2c0000, v195
	global_store_dwordx4 v222, v[14:17], s[70:71]
	s_cmp_eq_u32 s58, 1
	s_cbranch_scc0 .Lup_exit
; #define PG8_LAS __attribute__((address_space(3)))
;     __device__ __forceinline__ void operator()(const f32x4 (&acc)[2][2][4][2], const Unit& u, int wr, int wc, int fr, int fq) const {
;     ...
;                 if (samp) {
;                     const int bs = (row - MP) >> 4;
; #pragma unroll
;                     for (int n = 0; n < 2; ++n) { const f32x4 s0 = *(const f32x4*)(state + ((size_t)bs * 2 + 0) * DFF + cgc + 4 * n), s1 = *(const f32x4*)(state + ((size_t)bs * 2 + 1) * DFF + cgc + 4 * n);
;                         w1[n] = s1; w2[n] = fr == 0 ? s0 : s1; }
;                 } else if (m == 0) {
;                     if (blk > 0) {
; #pragma unroll
;                         for (int n = 0; n < 2; ++n) { const f32x4 c14 = *(const PG8_LAS f32x4*)(xbuf + ((blk - 1) * 2 + 0) * 128 + cl + 4 * n), c15 = *(const PG8_LAS f32x4*)(xbuf + ((blk - 1) * 2 + 1) * 128 + cl + 4 * n);
;                             w1[n] = c15; w2[n] = fr == 0 ? c14 : c15; }
;                     } else { w1[0] = w1[1] = w2[0] = w2[1] = (f32x4){0.f, 0.f, 0.f, 0.f}; }
;                 } else {
; #pragma unroll
;                     for (int n = 0; n < 2; ++n)
; #pragma unroll
;                         for (int i = 0; i < 4; ++i) { const float ap = acc[ai][0][m - 1][n][i]; w1[n][i] = dppf<0x10F>(ap); w2[n][i] = dppf<0x10E>(ap); }
;                 }
;                 f32x4 hv[2];
; #pragma unroll
;                 for (int n = 0; n < 2; ++n) {
;                     const f32x4 a = acc[ai][0][m][n], b = acc[ai][1][m][n];
; #pragma unroll
;                     for (int i = 0; i < 4; ++i) {
;                         const float s1 = dppf<0x111>(a[i]), s2 = dppf<0x112>(a[i]);
;                         const float p1 = fr >= 1 ? s1 : w1[n][i], p2 = fr >= 2 ? s2 : w2[n][i];
;                         const float ac = cw0[n][i] * p2 + cw1[n][i] * p1 + cw2[n][i] * a[i] + cb[n][i];
;                         hv[n][i] = gelu_tanh(ac) * b[i];
;                     }
;                 }
;                 *(u32x4*)(hh + (size_t)row * DFF + cgc) = pack8(hv[0], hv[1]);
;                 if (samp) {
;                     if (fr >= 14) { const int bs = (row - MP) >> 4; float* p = out + O_CVS + ((size_t)bs * 2 + (fr - 14)) * DFF + cgc; *(f32x4*)p = acc[ai][0][m][0]; *(f32x4*)(p + 4) = acc[ai][0][m][1]; }
;                 } else {
	s_lshl_b32 s59, s56, 16
	s_add_u32 s72, s76, 0x32e00000
	s_addc_u32 s73, s77, 0
	s_add_u32 s72, s72, s59
	s_addc_u32 s73, s73, 0
	s_mov_b32 exec_lo, 0xc000c000
	s_mov_b32 exec_hi, 0xc000c000
	global_store_dwordx4 v196, v[6:9], s[72:73]
	global_store_dwordx4 v196, v[2:5], s[72:73] offset:16
	s_and_b32 s59, s56, 31
	s_cmp_eq_u32 s59, 31
	s_cbranch_scc0 .Lup_exit
	s_lshr_b32 s59, s56, 5
	s_lshl_b32 s59, s59, 16
	s_add_u32 s72, s78, 0x18480000
	s_addc_u32 s73, s79, 0
	s_add_u32 s72, s72, s59
	s_addc_u32 s73, s73, 0
	global_store_dwordx4 v196, v[6:9], s[72:73]
	global_store_dwordx4 v196, v[2:5], s[72:73] offset:16
	s_branch .Lup_exit
.Lup_samp:
	v_readlane_b32 s74, v251, 17
	v_readlane_b32 s75, v251, 18
	s_sub_u32 s59, s56, 64
	s_lshl_b32 s59, s59, 4
	s_lshl_b32 s31, s58, 2
	s_add_u32 s59, s59, s31
	s_lshl_b32 s59, s59, 16
	s_add_u32 s74, s74, s59
	s_addc_u32 s75, s75, 0
	s_add_u32 s72, s78, 0x18ca4000
	s_addc_u32 s73, s79, 0
	s_add_u32 s72, s72, s59
	s_addc_u32 s73, s73, 0
	s_waitcnt vmcnt(0)
	s_mov_b64 s[86:87], s[74:75]
	global_load_dwordx4 v[162:165], v196, s[86:87]
	global_load_dwordx4 v[166:169], v196, s[86:87] offset:16
	s_mov_b64 s[86:87], s[72:73]
	s_mov_b32 exec_lo, 0xc000c000
	s_mov_b32 exec_hi, 0xc000c000
	global_store_dwordx4 v196, v[150:153], s[86:87]
	global_store_dwordx4 v196, v[146:149], s[86:87] offset:16
	s_mov_b64 exec, -1
	s_waitcnt vmcnt(2)
	v_pk_fma_f32 v[214:215], v[66:67], v[150:151], v[74:75]
	v_pk_fma_f32 v[216:217], v[68:69], v[152:153], v[76:77]
	v_fmac_f32_dpp v214, v150, v50 row_shr:1 row_mask:0xf bank_mask:0xf
	v_fmac_f32_dpp v215, v151, v51 row_shr:1 row_mask:0xf bank_mask:0xf
	v_fmac_f32_dpp v216, v152, v52 row_shr:1 row_mask:0xf bank_mask:0xf
	v_fmac_f32_dpp v217, v153, v53 row_shr:1 row_mask:0xf bank_mask:0xf
	v_fmac_f32_dpp v214, v162, v50 row_shl:15 row_mask:0xf bank_mask:0xf
	v_fmac_f32_dpp v215, v163, v51 row_shl:15 row_mask:0xf bank_mask:0xf
	v_fmac_f32_dpp v216, v164, v52 row_shl:15 row_mask:0xf bank_mask:0xf
	v_fmac_f32_dpp v217, v165, v53 row_shl:15 row_mask:0xf bank_mask:0xf
	v_fmac_f32_dpp v214, v150, v42 row_shr:2 row_mask:0xf bank_mask:0xf
	v_fmac_f32_dpp v215, v151, v43 row_shr:2 row_mask:0xf bank_mask:0xf
	v_fmac_f32_dpp v216, v152, v44 row_shr:2 row_mask:0xf bank_mask:0xf
	v_fmac_f32_dpp v217, v153, v45 row_shr:2 row_mask:0xf bank_mask:0xf
	v_fmac_f32_dpp v214, v162, v42 row_shl:14 row_mask:0xf bank_mask:0xf
	v_fmac_f32_dpp v215, v163, v43 row_shl:14 row_mask:0xf bank_mask:0xf
	v_fmac_f32_dpp v216, v164, v44 row_shl:14 row_mask:0xf bank_mask:0xf
	v_fmac_f32_dpp v217, v165, v45 row_shl:14 row_mask:0xf bank_mask:0xf
	v_pk_mul_f32 v[218:219], v[214:215], v[226:227] op_sel_hi:[1,0]
	v_pk_mul_f32 v[220:221], v[216:217], v[226:227] op_sel_hi:[1,0]
	v_pk_mul_f32 v[222:223], v[214:215], v[228:229] op_sel_hi:[1,0]
	v_pk_mul_f32 v[224:225], v[216:217], v[228:229] op_sel_hi:[1,0]
	v_pk_fma_f32 v[218:219], v[214:215], v[218:219], 1.0 op_sel_hi:[1,1,0]
	v_pk_fma_f32 v[220:221], v[216:217], v[220:221], 1.0 op_sel_hi:[1,1,0]
	v_pk_mul_f32 v[222:223], v[222:223], v[218:219] neg_lo:[0,1] neg_hi:[0,1]
	v_pk_mul_f32 v[224:225], v[224:225], v[220:221] neg_lo:[0,1] neg_hi:[0,1]
	v_pk_mul_f32 v[222:223], v[222:223], v[230:231] op_sel_hi:[1,0]
	v_pk_mul_f32 v[224:225], v[224:225], v[230:231] op_sel_hi:[1,0]
	v_exp_f32_e32 v222, v222
	v_exp_f32_e32 v223, v223
	v_exp_f32_e32 v224, v224
	v_exp_f32_e32 v225, v225
	v_pk_add_f32 v[222:223], v[222:223], 1.0 op_sel_hi:[1,0]
	v_pk_add_f32 v[224:225], v[224:225], 1.0 op_sel_hi:[1,0]
	v_rcp_f32_e32 v222, v222
	v_rcp_f32_e32 v223, v223
	v_rcp_f32_e32 v224, v224
	v_rcp_f32_e32 v225, v225
	v_pk_mul_f32 v[218:219], v[214:215], v[222:223]
	v_pk_mul_f32 v[220:221], v[216:217], v[224:225]
	v_pk_mul_f32 v[158:159], v[158:159], v[218:219]
	v_pk_mul_f32 v[160:161], v[160:161], v[220:221]
	v_pk_fma_f32 v[214:215], v[70:71], v[146:147], v[78:79]
	v_pk_fma_f32 v[216:217], v[72:73], v[148:149], v[80:81]
	v_fmac_f32_dpp v214, v146, v54 row_shr:1 row_mask:0xf bank_mask:0xf
	v_fmac_f32_dpp v215, v147, v55 row_shr:1 row_mask:0xf bank_mask:0xf
	v_fmac_f32_dpp v216, v148, v56 row_shr:1 row_mask:0xf bank_mask:0xf
	v_fmac_f32_dpp v217, v149, v57 row_shr:1 row_mask:0xf bank_mask:0xf
	v_fmac_f32_dpp v214, v166, v54 row_shl:15 row_mask:0xf bank_mask:0xf
	v_fmac_f32_dpp v215, v167, v55 row_shl:15 row_mask:0xf bank_mask:0xf
	v_fmac_f32_dpp v216, v168, v56 row_shl:15 row_mask:0xf bank_mask:0xf
	v_fmac_f32_dpp v217, v169, v57 row_shl:15 row_mask:0xf bank_mask:0xf
	v_fmac_f32_dpp v214, v146, v46 row_shr:2 row_mask:0xf bank_mask:0xf
	v_fmac_f32_dpp v215, v147, v47 row_shr:2 row_mask:0xf bank_mask:0xf
	v_fmac_f32_dpp v216, v148, v48 row_shr:2 row_mask:0xf bank_mask:0xf
	v_fmac_f32_dpp v217, v149, v49 row_shr:2 row_mask:0xf bank_mask:0xf
	v_fmac_f32_dpp v214, v166, v46 row_shl:14 row_mask:0xf bank_mask:0xf
	v_fmac_f32_dpp v215, v167, v47 row_shl:14 row_mask:0xf bank_mask:0xf
	v_fmac_f32_dpp v216, v168, v48 row_shl:14 row_mask:0xf bank_mask:0xf
	v_fmac_f32_dpp v217, v169, v49 row_shl:14 row_mask:0xf bank_mask:0xf
	v_pk_mul_f32 v[218:219], v[214:215], v[226:227] op_sel_hi:[1,0]
	v_pk_mul_f32 v[220:221], v[216:217], v[226:227] op_sel_hi:[1,0]
	v_pk_mul_f32 v[222:223], v[214:215], v[228:229] op_sel_hi:[1,0]
	v_pk_mul_f32 v[224:225], v[216:217], v[228:229] op_sel_hi:[1,0]
	v_pk_fma_f32 v[218:219], v[214:215], v[218:219], 1.0 op_sel_hi:[1,1,0]
	v_pk_fma_f32 v[220:221], v[216:217], v[220:221], 1.0 op_sel_hi:[1,1,0]
	v_pk_mul_f32 v[222:223], v[222:223], v[218:219] neg_lo:[0,1] neg_hi:[0,1]
	v_pk_mul_f32 v[224:225], v[224:225], v[220:221] neg_lo:[0,1] neg_hi:[0,1]
	v_pk_mul_f32 v[222:223], v[222:223], v[230:231] op_sel_hi:[1,0]
	v_pk_mul_f32 v[224:225], v[224:225], v[230:231] op_sel_hi:[1,0]
	v_exp_f32_e32 v222, v222
	v_exp_f32_e32 v223, v223
	v_exp_f32_e32 v224, v224
	v_exp_f32_e32 v225, v225
	v_pk_add_f32 v[222:223], v[222:223], 1.0 op_sel_hi:[1,0]
	v_pk_add_f32 v[224:225], v[224:225], 1.0 op_sel_hi:[1,0]
	v_rcp_f32_e32 v222, v222
	v_rcp_f32_e32 v223, v223
	v_rcp_f32_e32 v224, v224
	v_rcp_f32_e32 v225, v225
	v_pk_mul_f32 v[218:219], v[214:215], v[222:223]
	v_pk_mul_f32 v[220:221], v[216:217], v[224:225]
	v_pk_mul_f32 v[154:155], v[154:155], v[218:219]
	v_pk_mul_f32 v[156:157], v[156:157], v[220:221]
	v_cvt_pk_bf16_f32 v158, v158, v159
	v_cvt_pk_bf16_f32 v159, v160, v161
	v_cvt_pk_bf16_f32 v160, v154, v155
	v_cvt_pk_bf16_f32 v161, v156, v157
	v_mov_b32_e32 v222, v195
	global_store_dwordx4 v222, v[158:161], s[70:71]
	s_add_u32 s86, s74, 0x10000
	s_addc_u32 s87, s75, 0
	global_load_dwordx4 v[162:165], v196, s[86:87]
	global_load_dwordx4 v[166:169], v196, s[86:87] offset:16
	s_add_u32 s86, s72, 0x10000
	s_addc_u32 s87, s73, 0
	s_mov_b32 exec_lo, 0xc000c000
	s_mov_b32 exec_hi, 0xc000c000
	global_store_dwordx4 v196, v[134:137], s[86:87]
	global_store_dwordx4 v196, v[130:133], s[86:87] offset:16
	s_mov_b64 exec, -1
	s_waitcnt vmcnt(2)
; __device__ __forceinline__ u32x4 pack8(const f32x4 a, const f32x4 b) { u32x4 w; w.x = cvt_pk_bf16(a[0], a[1]); w.y = cvt_pk_bf16(a[2], a[3]); w.z = cvt_pk_bf16(b[0], b[1]); w.w = cvt_pk_bf16(b[2], b[3]); return w; }
; template <int CTRL> __device__ __forceinline__ float dppf(float v) { return __builtin_bit_cast(float, __builtin_amdgcn_update_dpp(0, __builtin_bit_cast(int, v), CTRL, 0xf, 0xf, true)); }
;     __device__ __forceinline__ void operator()(const f32x4 (&acc)[2][2][4][2], const Unit& u, int wr, int wc, int fr, int fq) const {
;     ...
;                 f32x4 hv[2];
; #pragma unroll
;                 for (int n = 0; n < 2; ++n) {
;                     const f32x4 a = acc[ai][0][m][n], b = acc[ai][1][m][n];
; #pragma unroll
;                     for (int i = 0; i < 4; ++i) {
;                         const float s1 = dppf<0x111>(a[i]), s2 = dppf<0x112>(a[i]);
;                         const float p1 = fr >= 1 ? s1 : w1[n][i], p2 = fr >= 2 ? s2 : w2[n][i];
;                         const float ac = cw0[n][i] * p2 + cw1[n][i] * p1 + cw2[n][i] * a[i] + cb[n][i];
;                         hv[n][i] = gelu_tanh(ac) * b[i];
;                     }
;                 }
;                 *(u32x4*)(hh + (size_t)row * DFF + cgc) = pack8(hv[0], hv[1]);
;                 if (samp) {
;                     if (fr >= 14) { const int bs = (row - MP) >> 4; float* p = out + O_CVS + ((size_t)bs * 2 + (fr - 14)) * DFF + cgc; *(f32x4*)p = acc[ai][0][m][0]; *(f32x4*)(p + 4) = acc[ai][0][m][1]; }
	v_pk_fma_f32 v[214:215], v[66:67], v[134:135], v[74:75]
	v_pk_fma_f32 v[216:217], v[68:69], v[136:137], v[76:77]
	v_fmac_f32_dpp v214, v134, v50 row_shr:1 row_mask:0xf bank_mask:0xf
	v_fmac_f32_dpp v215, v135, v51 row_shr:1 row_mask:0xf bank_mask:0xf
	v_fmac_f32_dpp v216, v136, v52 row_shr:1 row_mask:0xf bank_mask:0xf
	v_fmac_f32_dpp v217, v137, v53 row_shr:1 row_mask:0xf bank_mask:0xf
	v_fmac_f32_dpp v214, v162, v50 row_shl:15 row_mask:0xf bank_mask:0xf
	v_fmac_f32_dpp v215, v163, v51 row_shl:15 row_mask:0xf bank_mask:0xf
	v_fmac_f32_dpp v216, v164, v52 row_shl:15 row_mask:0xf bank_mask:0xf
	v_fmac_f32_dpp v217, v165, v53 row_shl:15 row_mask:0xf bank_mask:0xf
	v_fmac_f32_dpp v214, v134, v42 row_shr:2 row_mask:0xf bank_mask:0xf
	v_fmac_f32_dpp v215, v135, v43 row_shr:2 row_mask:0xf bank_mask:0xf
	v_fmac_f32_dpp v216, v136, v44 row_shr:2 row_mask:0xf bank_mask:0xf
	v_fmac_f32_dpp v217, v137, v45 row_shr:2 row_mask:0xf bank_mask:0xf
	v_fmac_f32_dpp v214, v162, v42 row_shl:14 row_mask:0xf bank_mask:0xf
	v_fmac_f32_dpp v215, v163, v43 row_shl:14 row_mask:0xf bank_mask:0xf
	v_fmac_f32_dpp v216, v164, v44 row_shl:14 row_mask:0xf bank_mask:0xf
	v_fmac_f32_dpp v217, v165, v45 row_shl:14 row_mask:0xf bank_mask:0xf
	v_pk_mul_f32 v[218:219], v[214:215], v[226:227] op_sel_hi:[1,0]
	v_pk_mul_f32 v[220:221], v[216:217], v[226:227] op_sel_hi:[1,0]
	v_pk_mul_f32 v[222:223], v[214:215], v[228:229] op_sel_hi:[1,0]
	v_pk_mul_f32 v[224:225], v[216:217], v[228:229] op_sel_hi:[1,0]
	v_pk_fma_f32 v[218:219], v[214:215], v[218:219], 1.0 op_sel_hi:[1,1,0]
	v_pk_fma_f32 v[220:221], v[216:217], v[220:221], 1.0 op_sel_hi:[1,1,0]
	v_pk_mul_f32 v[222:223], v[222:223], v[218:219] neg_lo:[0,1] neg_hi:[0,1]
	v_pk_mul_f32 v[224:225], v[224:225], v[220:221] neg_lo:[0,1] neg_hi:[0,1]
	v_pk_mul_f32 v[222:223], v[222:223], v[230:231] op_sel_hi:[1,0]
	v_pk_mul_f32 v[224:225], v[224:225], v[230:231] op_sel_hi:[1,0]
	v_exp_f32_e32 v222, v222
	v_exp_f32_e32 v223, v223
	v_exp_f32_e32 v224, v224
	v_exp_f32_e32 v225, v225
	v_pk_add_f32 v[222:223], v[222:223], 1.0 op_sel_hi:[1,0]
	v_pk_add_f32 v[224:225], v[224:225], 1.0 op_sel_hi:[1,0]
	v_rcp_f32_e32 v222, v222
	v_rcp_f32_e32 v223, v223
	v_rcp_f32_e32 v224, v224
	v_rcp_f32_e32 v225, v225
	v_pk_mul_f32 v[218:219], v[214:215], v[222:223]
	v_pk_mul_f32 v[220:221], v[216:217], v[224:225]
	v_pk_mul_f32 v[142:143], v[142:143], v[218:219]
	v_pk_mul_f32 v[144:145], v[144:145], v[220:221]
	v_pk_fma_f32 v[214:215], v[70:71], v[130:131], v[78:79]
	v_pk_fma_f32 v[216:217], v[72:73], v[132:133], v[80:81]
	v_fmac_f32_dpp v214, v130, v54 row_shr:1 row_mask:0xf bank_mask:0xf
	v_fmac_f32_dpp v215, v131, v55 row_shr:1 row_mask:0xf bank_mask:0xf
	v_fmac_f32_dpp v216, v132, v56 row_shr:1 row_mask:0xf bank_mask:0xf
	v_fmac_f32_dpp v217, v133, v57 row_shr:1 row_mask:0xf bank_mask:0xf
	v_fmac_f32_dpp v214, v166, v54 row_shl:15 row_mask:0xf bank_mask:0xf
	v_fmac_f32_dpp v215, v167, v55 row_shl:15 row_mask:0xf bank_mask:0xf
	v_fmac_f32_dpp v216, v168, v56 row_shl:15 row_mask:0xf bank_mask:0xf
	v_fmac_f32_dpp v217, v169, v57 row_shl:15 row_mask:0xf bank_mask:0xf
	v_fmac_f32_dpp v214, v130, v46 row_shr:2 row_mask:0xf bank_mask:0xf
	v_fmac_f32_dpp v215, v131, v47 row_shr:2 row_mask:0xf bank_mask:0xf
	v_fmac_f32_dpp v216, v132, v48 row_shr:2 row_mask:0xf bank_mask:0xf
	v_fmac_f32_dpp v217, v133, v49 row_shr:2 row_mask:0xf bank_mask:0xf
	v_fmac_f32_dpp v214, v166, v46 row_shl:14 row_mask:0xf bank_mask:0xf
	v_fmac_f32_dpp v215, v167, v47 row_shl:14 row_mask:0xf bank_mask:0xf
	v_fmac_f32_dpp v216, v168, v48 row_shl:14 row_mask:0xf bank_mask:0xf
	v_fmac_f32_dpp v217, v169, v49 row_shl:14 row_mask:0xf bank_mask:0xf
	v_pk_mul_f32 v[218:219], v[214:215], v[226:227] op_sel_hi:[1,0]
	v_pk_mul_f32 v[220:221], v[216:217], v[226:227] op_sel_hi:[1,0]
	v_pk_mul_f32 v[222:223], v[214:215], v[228:229] op_sel_hi:[1,0]
	v_pk_mul_f32 v[224:225], v[216:217], v[228:229] op_sel_hi:[1,0]
	v_pk_fma_f32 v[218:219], v[214:215], v[218:219], 1.0 op_sel_hi:[1,1,0]
	v_pk_fma_f32 v[220:221], v[216:217], v[220:221], 1.0 op_sel_hi:[1,1,0]
	v_pk_mul_f32 v[222:223], v[222:223], v[218:219] neg_lo:[0,1] neg_hi:[0,1]
	v_pk_mul_f32 v[224:225], v[224:225], v[220:221] neg_lo:[0,1] neg_hi:[0,1]
	v_pk_mul_f32 v[222:223], v[222:223], v[230:231] op_sel_hi:[1,0]
	v_pk_mul_f32 v[224:225], v[224:225], v[230:231] op_sel_hi:[1,0]
	v_exp_f32_e32 v222, v222
	v_exp_f32_e32 v223, v223
	v_exp_f32_e32 v224, v224
	v_exp_f32_e32 v225, v225
	v_pk_add_f32 v[222:223], v[222:223], 1.0 op_sel_hi:[1,0]
	v_pk_add_f32 v[224:225], v[224:225], 1.0 op_sel_hi:[1,0]
	v_rcp_f32_e32 v222, v222
	v_rcp_f32_e32 v223, v223
	v_rcp_f32_e32 v224, v224
	v_rcp_f32_e32 v225, v225
	v_pk_mul_f32 v[218:219], v[214:215], v[222:223]
	v_pk_mul_f32 v[220:221], v[216:217], v[224:225]
	v_pk_mul_f32 v[138:139], v[138:139], v[218:219]
	v_pk_mul_f32 v[140:141], v[140:141], v[220:221]
	v_cvt_pk_bf16_f32 v142, v142, v143
	v_cvt_pk_bf16_f32 v143, v144, v145
	v_cvt_pk_bf16_f32 v144, v138, v139
	v_cvt_pk_bf16_f32 v145, v140, v141
	v_add_u32_e32 v222, 0x40000, v195
	global_store_dwordx4 v222, v[142:145], s[70:71]
	s_add_u32 s86, s74, 0x20000
	s_addc_u32 s87, s75, 0
	global_load_dwordx4 v[162:165], v196, s[86:87]
	global_load_dwordx4 v[166:169], v196, s[86:87] offset:16
	s_add_u32 s86, s72, 0x20000
	s_addc_u32 s87, s73, 0
	s_mov_b32 exec_lo, 0xc000c000
	s_mov_b32 exec_hi, 0xc000c000
	global_store_dwordx4 v196, v[118:121], s[86:87]
	global_store_dwordx4 v196, v[114:117], s[86:87] offset:16
	s_mov_b64 exec, -1
	s_waitcnt vmcnt(2)
; __device__ __forceinline__ u32x4 pack8(const f32x4 a, const f32x4 b) { u32x4 w; w.x = cvt_pk_bf16(a[0], a[1]); w.y = cvt_pk_bf16(a[2], a[3]); w.z = cvt_pk_bf16(b[0], b[1]); w.w = cvt_pk_bf16(b[2], b[3]); return w; }
; template <int CTRL> __device__ __forceinline__ float dppf(float v) { return __builtin_bit_cast(float, __builtin_amdgcn_update_dpp(0, __builtin_bit_cast(int, v), CTRL, 0xf, 0xf, true)); }
;     __device__ __forceinline__ void operator()(const f32x4 (&acc)[2][2][4][2], const Unit& u, int wr, int wc, int fr, int fq) const {
;     ...
;                 f32x4 hv[2];
; #pragma unroll
;                 for (int n = 0; n < 2; ++n) {
;                     const f32x4 a = acc[ai][0][m][n], b = acc[ai][1][m][n];
; #pragma unroll
;                     for (int i = 0; i < 4; ++i) {
;                         const float s1 = dppf<0x111>(a[i]), s2 = dppf<0x112>(a[i]);
;                         const float p1 = fr >= 1 ? s1 : w1[n][i], p2 = fr >= 2 ? s2 : w2[n][i];
;                         const float ac = cw0[n][i] * p2 + cw1[n][i] * p1 + cw2[n][i] * a[i] + cb[n][i];
;                         hv[n][i] = gelu_tanh(ac) * b[i];
;                     }
;                 }
;                 *(u32x4*)(hh + (size_t)row * DFF + cgc) = pack8(hv[0], hv[1]);
;                 if (samp) {
;                     if (fr >= 14) { const int bs = (row - MP) >> 4; float* p = out + O_CVS + ((size_t)bs * 2 + (fr - 14)) * DFF + cgc; *(f32x4*)p = acc[ai][0][m][0]; *(f32x4*)(p + 4) = acc[ai][0][m][1]; }
	v_pk_fma_f32 v[214:215], v[66:67], v[118:119], v[74:75]
	v_pk_fma_f32 v[216:217], v[68:69], v[120:121], v[76:77]
	v_fmac_f32_dpp v214, v118, v50 row_shr:1 row_mask:0xf bank_mask:0xf
	v_fmac_f32_dpp v215, v119, v51 row_shr:1 row_mask:0xf bank_mask:0xf
	v_fmac_f32_dpp v216, v120, v52 row_shr:1 row_mask:0xf bank_mask:0xf
	v_fmac_f32_dpp v217, v121, v53 row_shr:1 row_mask:0xf bank_mask:0xf
	v_fmac_f32_dpp v214, v162, v50 row_shl:15 row_mask:0xf bank_mask:0xf
	v_fmac_f32_dpp v215, v163, v51 row_shl:15 row_mask:0xf bank_mask:0xf
	v_fmac_f32_dpp v216, v164, v52 row_shl:15 row_mask:0xf bank_mask:0xf
	v_fmac_f32_dpp v217, v165, v53 row_shl:15 row_mask:0xf bank_mask:0xf
	v_fmac_f32_dpp v214, v118, v42 row_shr:2 row_mask:0xf bank_mask:0xf
	v_fmac_f32_dpp v215, v119, v43 row_shr:2 row_mask:0xf bank_mask:0xf
	v_fmac_f32_dpp v216, v120, v44 row_shr:2 row_mask:0xf bank_mask:0xf
	v_fmac_f32_dpp v217, v121, v45 row_shr:2 row_mask:0xf bank_mask:0xf
	v_fmac_f32_dpp v214, v162, v42 row_shl:14 row_mask:0xf bank_mask:0xf
	v_fmac_f32_dpp v215, v163, v43 row_shl:14 row_mask:0xf bank_mask:0xf
	v_fmac_f32_dpp v216, v164, v44 row_shl:14 row_mask:0xf bank_mask:0xf
	v_fmac_f32_dpp v217, v165, v45 row_shl:14 row_mask:0xf bank_mask:0xf
	v_pk_mul_f32 v[218:219], v[214:215], v[226:227] op_sel_hi:[1,0]
	v_pk_mul_f32 v[220:221], v[216:217], v[226:227] op_sel_hi:[1,0]
	v_pk_mul_f32 v[222:223], v[214:215], v[228:229] op_sel_hi:[1,0]
	v_pk_mul_f32 v[224:225], v[216:217], v[228:229] op_sel_hi:[1,0]
	v_pk_fma_f32 v[218:219], v[214:215], v[218:219], 1.0 op_sel_hi:[1,1,0]
	v_pk_fma_f32 v[220:221], v[216:217], v[220:221], 1.0 op_sel_hi:[1,1,0]
	v_pk_mul_f32 v[222:223], v[222:223], v[218:219] neg_lo:[0,1] neg_hi:[0,1]
	v_pk_mul_f32 v[224:225], v[224:225], v[220:221] neg_lo:[0,1] neg_hi:[0,1]
	v_pk_mul_f32 v[222:223], v[222:223], v[230:231] op_sel_hi:[1,0]
	v_pk_mul_f32 v[224:225], v[224:225], v[230:231] op_sel_hi:[1,0]
	v_exp_f32_e32 v222, v222
	v_exp_f32_e32 v223, v223
	v_exp_f32_e32 v224, v224
	v_exp_f32_e32 v225, v225
	v_pk_add_f32 v[222:223], v[222:223], 1.0 op_sel_hi:[1,0]
	v_pk_add_f32 v[224:225], v[224:225], 1.0 op_sel_hi:[1,0]
	v_rcp_f32_e32 v222, v222
	v_rcp_f32_e32 v223, v223
	v_rcp_f32_e32 v224, v224
	v_rcp_f32_e32 v225, v225
	v_pk_mul_f32 v[218:219], v[214:215], v[222:223]
	v_pk_mul_f32 v[220:221], v[216:217], v[224:225]
	v_pk_mul_f32 v[126:127], v[126:127], v[218:219]
	v_pk_mul_f32 v[128:129], v[128:129], v[220:221]
	v_pk_fma_f32 v[214:215], v[70:71], v[114:115], v[78:79]
	v_pk_fma_f32 v[216:217], v[72:73], v[116:117], v[80:81]
	v_fmac_f32_dpp v214, v114, v54 row_shr:1 row_mask:0xf bank_mask:0xf
	v_fmac_f32_dpp v215, v115, v55 row_shr:1 row_mask:0xf bank_mask:0xf
	v_fmac_f32_dpp v216, v116, v56 row_shr:1 row_mask:0xf bank_mask:0xf
	v_fmac_f32_dpp v217, v117, v57 row_shr:1 row_mask:0xf bank_mask:0xf
	v_fmac_f32_dpp v214, v166, v54 row_shl:15 row_mask:0xf bank_mask:0xf
	v_fmac_f32_dpp v215, v167, v55 row_shl:15 row_mask:0xf bank_mask:0xf
	v_fmac_f32_dpp v216, v168, v56 row_shl:15 row_mask:0xf bank_mask:0xf
	v_fmac_f32_dpp v217, v169, v57 row_shl:15 row_mask:0xf bank_mask:0xf
	v_fmac_f32_dpp v214, v114, v46 row_shr:2 row_mask:0xf bank_mask:0xf
	v_fmac_f32_dpp v215, v115, v47 row_shr:2 row_mask:0xf bank_mask:0xf
	v_fmac_f32_dpp v216, v116, v48 row_shr:2 row_mask:0xf bank_mask:0xf
	v_fmac_f32_dpp v217, v117, v49 row_shr:2 row_mask:0xf bank_mask:0xf
	v_fmac_f32_dpp v214, v166, v46 row_shl:14 row_mask:0xf bank_mask:0xf
	v_fmac_f32_dpp v215, v167, v47 row_shl:14 row_mask:0xf bank_mask:0xf
	v_fmac_f32_dpp v216, v168, v48 row_shl:14 row_mask:0xf bank_mask:0xf
	v_fmac_f32_dpp v217, v169, v49 row_shl:14 row_mask:0xf bank_mask:0xf
	v_pk_mul_f32 v[218:219], v[214:215], v[226:227] op_sel_hi:[1,0]
	v_pk_mul_f32 v[220:221], v[216:217], v[226:227] op_sel_hi:[1,0]
	v_pk_mul_f32 v[222:223], v[214:215], v[228:229] op_sel_hi:[1,0]
	v_pk_mul_f32 v[224:225], v[216:217], v[228:229] op_sel_hi:[1,0]
	v_pk_fma_f32 v[218:219], v[214:215], v[218:219], 1.0 op_sel_hi:[1,1,0]
	v_pk_fma_f32 v[220:221], v[216:217], v[220:221], 1.0 op_sel_hi:[1,1,0]
	v_pk_mul_f32 v[222:223], v[222:223], v[218:219] neg_lo:[0,1] neg_hi:[0,1]
	v_pk_mul_f32 v[224:225], v[224:225], v[220:221] neg_lo:[0,1] neg_hi:[0,1]
	v_pk_mul_f32 v[222:223], v[222:223], v[230:231] op_sel_hi:[1,0]
	v_pk_mul_f32 v[224:225], v[224:225], v[230:231] op_sel_hi:[1,0]
	v_exp_f32_e32 v222, v222
	v_exp_f32_e32 v223, v223
	v_exp_f32_e32 v224, v224
	v_exp_f32_e32 v225, v225
	v_pk_add_f32 v[222:223], v[222:223], 1.0 op_sel_hi:[1,0]
	v_pk_add_f32 v[224:225], v[224:225], 1.0 op_sel_hi:[1,0]
	v_rcp_f32_e32 v222, v222
	v_rcp_f32_e32 v223, v223
	v_rcp_f32_e32 v224, v224
	v_rcp_f32_e32 v225, v225
	v_pk_mul_f32 v[218:219], v[214:215], v[222:223]
	v_pk_mul_f32 v[220:221], v[216:217], v[224:225]
	v_pk_mul_f32 v[122:123], v[122:123], v[218:219]
	v_pk_mul_f32 v[124:125], v[124:125], v[220:221]
	v_cvt_pk_bf16_f32 v126, v126, v127
	v_cvt_pk_bf16_f32 v127, v128, v129
	v_cvt_pk_bf16_f32 v128, v122, v123
	v_cvt_pk_bf16_f32 v129, v124, v125
	v_add_u32_e32 v222, 0x80000, v195
	global_store_dwordx4 v222, v[126:129], s[70:71]
	s_add_u32 s86, s74, 0x30000
	s_addc_u32 s87, s75, 0
	global_load_dwordx4 v[162:165], v196, s[86:87]
	global_load_dwordx4 v[166:169], v196, s[86:87] offset:16
	s_add_u32 s86, s72, 0x30000
	s_addc_u32 s87, s73, 0
	s_mov_b32 exec_lo, 0xc000c000
	s_mov_b32 exec_hi, 0xc000c000
	global_store_dwordx4 v196, v[102:105], s[86:87]
	global_store_dwordx4 v196, v[98:101], s[86:87] offset:16
	s_mov_b64 exec, -1
	s_waitcnt vmcnt(2)
; __device__ __forceinline__ u32x4 pack8(const f32x4 a, const f32x4 b) { u32x4 w; w.x = cvt_pk_bf16(a[0], a[1]); w.y = cvt_pk_bf16(a[2], a[3]); w.z = cvt_pk_bf16(b[0], b[1]); w.w = cvt_pk_bf16(b[2], b[3]); return w; }
; template <int CTRL> __device__ __forceinline__ float dppf(float v) { return __builtin_bit_cast(float, __builtin_amdgcn_update_dpp(0, __builtin_bit_cast(int, v), CTRL, 0xf, 0xf, true)); }
;     __device__ __forceinline__ void operator()(const f32x4 (&acc)[2][2][4][2], const Unit& u, int wr, int wc, int fr, int fq) const {
;     ...
;                 f32x4 hv[2];
; #pragma unroll
;                 for (int n = 0; n < 2; ++n) {
;                     const f32x4 a = acc[ai][0][m][n], b = acc[ai][1][m][n];
; #pragma unroll
;                     for (int i = 0; i < 4; ++i) {
;                         const float s1 = dppf<0x111>(a[i]), s2 = dppf<0x112>(a[i]);
;                         const float p1 = fr >= 1 ? s1 : w1[n][i], p2 = fr >= 2 ? s2 : w2[n][i];
;                         const float ac = cw0[n][i] * p2 + cw1[n][i] * p1 + cw2[n][i] * a[i] + cb[n][i];
;                         hv[n][i] = gelu_tanh(ac) * b[i];
;                     }
;                 }
;                 *(u32x4*)(hh + (size_t)row * DFF + cgc) = pack8(hv[0], hv[1]);
;                 if (samp) {
;                     if (fr >= 14) { const int bs = (row - MP) >> 4; float* p = out + O_CVS + ((size_t)bs * 2 + (fr - 14)) * DFF + cgc; *(f32x4*)p = acc[ai][0][m][0]; *(f32x4*)(p + 4) = acc[ai][0][m][1]; }
	v_pk_fma_f32 v[214:215], v[66:67], v[102:103], v[74:75]
	v_pk_fma_f32 v[216:217], v[68:69], v[104:105], v[76:77]
	v_fmac_f32_dpp v214, v102, v50 row_shr:1 row_mask:0xf bank_mask:0xf
	v_fmac_f32_dpp v215, v103, v51 row_shr:1 row_mask:0xf bank_mask:0xf
	v_fmac_f32_dpp v216, v104, v52 row_shr:1 row_mask:0xf bank_mask:0xf
	v_fmac_f32_dpp v217, v105, v53 row_shr:1 row_mask:0xf bank_mask:0xf
	v_fmac_f32_dpp v214, v162, v50 row_shl:15 row_mask:0xf bank_mask:0xf
	v_fmac_f32_dpp v215, v163, v51 row_shl:15 row_mask:0xf bank_mask:0xf
	v_fmac_f32_dpp v216, v164, v52 row_shl:15 row_mask:0xf bank_mask:0xf
	v_fmac_f32_dpp v217, v165, v53 row_shl:15 row_mask:0xf bank_mask:0xf
	v_fmac_f32_dpp v214, v102, v42 row_shr:2 row_mask:0xf bank_mask:0xf
	v_fmac_f32_dpp v215, v103, v43 row_shr:2 row_mask:0xf bank_mask:0xf
	v_fmac_f32_dpp v216, v104, v44 row_shr:2 row_mask:0xf bank_mask:0xf
	v_fmac_f32_dpp v217, v105, v45 row_shr:2 row_mask:0xf bank_mask:0xf
	v_fmac_f32_dpp v214, v162, v42 row_shl:14 row_mask:0xf bank_mask:0xf
	v_fmac_f32_dpp v215, v163, v43 row_shl:14 row_mask:0xf bank_mask:0xf
	v_fmac_f32_dpp v216, v164, v44 row_shl:14 row_mask:0xf bank_mask:0xf
	v_fmac_f32_dpp v217, v165, v45 row_shl:14 row_mask:0xf bank_mask:0xf
	v_pk_mul_f32 v[218:219], v[214:215], v[226:227] op_sel_hi:[1,0]
	v_pk_mul_f32 v[220:221], v[216:217], v[226:227] op_sel_hi:[1,0]
	v_pk_mul_f32 v[222:223], v[214:215], v[228:229] op_sel_hi:[1,0]
	v_pk_mul_f32 v[224:225], v[216:217], v[228:229] op_sel_hi:[1,0]
	v_pk_fma_f32 v[218:219], v[214:215], v[218:219], 1.0 op_sel_hi:[1,1,0]
	v_pk_fma_f32 v[220:221], v[216:217], v[220:221], 1.0 op_sel_hi:[1,1,0]
	v_pk_mul_f32 v[222:223], v[222:223], v[218:219] neg_lo:[0,1] neg_hi:[0,1]
	v_pk_mul_f32 v[224:225], v[224:225], v[220:221] neg_lo:[0,1] neg_hi:[0,1]
	v_pk_mul_f32 v[222:223], v[222:223], v[230:231] op_sel_hi:[1,0]
	v_pk_mul_f32 v[224:225], v[224:225], v[230:231] op_sel_hi:[1,0]
	v_exp_f32_e32 v222, v222
	v_exp_f32_e32 v223, v223
	v_exp_f32_e32 v224, v224
	v_exp_f32_e32 v225, v225
	v_pk_add_f32 v[222:223], v[222:223], 1.0 op_sel_hi:[1,0]
	v_pk_add_f32 v[224:225], v[224:225], 1.0 op_sel_hi:[1,0]
	v_rcp_f32_e32 v222, v222
	v_rcp_f32_e32 v223, v223
	v_rcp_f32_e32 v224, v224
	v_rcp_f32_e32 v225, v225
	v_pk_mul_f32 v[218:219], v[214:215], v[222:223]
	v_pk_mul_f32 v[220:221], v[216:217], v[224:225]
	v_pk_mul_f32 v[110:111], v[110:111], v[218:219]
	v_pk_mul_f32 v[112:113], v[112:113], v[220:221]
	v_pk_fma_f32 v[214:215], v[70:71], v[98:99], v[78:79]
	v_pk_fma_f32 v[216:217], v[72:73], v[100:101], v[80:81]
	v_fmac_f32_dpp v214, v98, v54 row_shr:1 row_mask:0xf bank_mask:0xf
	v_fmac_f32_dpp v215, v99, v55 row_shr:1 row_mask:0xf bank_mask:0xf
	v_fmac_f32_dpp v216, v100, v56 row_shr:1 row_mask:0xf bank_mask:0xf
	v_fmac_f32_dpp v217, v101, v57 row_shr:1 row_mask:0xf bank_mask:0xf
	v_fmac_f32_dpp v214, v166, v54 row_shl:15 row_mask:0xf bank_mask:0xf
	v_fmac_f32_dpp v215, v167, v55 row_shl:15 row_mask:0xf bank_mask:0xf
	v_fmac_f32_dpp v216, v168, v56 row_shl:15 row_mask:0xf bank_mask:0xf
	v_fmac_f32_dpp v217, v169, v57 row_shl:15 row_mask:0xf bank_mask:0xf
	v_fmac_f32_dpp v214, v98, v46 row_shr:2 row_mask:0xf bank_mask:0xf
	v_fmac_f32_dpp v215, v99, v47 row_shr:2 row_mask:0xf bank_mask:0xf
	v_fmac_f32_dpp v216, v100, v48 row_shr:2 row_mask:0xf bank_mask:0xf
	v_fmac_f32_dpp v217, v101, v49 row_shr:2 row_mask:0xf bank_mask:0xf
	v_fmac_f32_dpp v214, v166, v46 row_shl:14 row_mask:0xf bank_mask:0xf
	v_fmac_f32_dpp v215, v167, v47 row_shl:14 row_mask:0xf bank_mask:0xf
	v_fmac_f32_dpp v216, v168, v48 row_shl:14 row_mask:0xf bank_mask:0xf
	v_fmac_f32_dpp v217, v169, v49 row_shl:14 row_mask:0xf bank_mask:0xf
	v_pk_mul_f32 v[218:219], v[214:215], v[226:227] op_sel_hi:[1,0]
	v_pk_mul_f32 v[220:221], v[216:217], v[226:227] op_sel_hi:[1,0]
	v_pk_mul_f32 v[222:223], v[214:215], v[228:229] op_sel_hi:[1,0]
	v_pk_mul_f32 v[224:225], v[216:217], v[228:229] op_sel_hi:[1,0]
	v_pk_fma_f32 v[218:219], v[214:215], v[218:219], 1.0 op_sel_hi:[1,1,0]
	v_pk_fma_f32 v[220:221], v[216:217], v[220:221], 1.0 op_sel_hi:[1,1,0]
	v_pk_mul_f32 v[222:223], v[222:223], v[218:219] neg_lo:[0,1] neg_hi:[0,1]
	v_pk_mul_f32 v[224:225], v[224:225], v[220:221] neg_lo:[0,1] neg_hi:[0,1]
	v_pk_mul_f32 v[222:223], v[222:223], v[230:231] op_sel_hi:[1,0]
	v_pk_mul_f32 v[224:225], v[224:225], v[230:231] op_sel_hi:[1,0]
	v_exp_f32_e32 v222, v222
	v_exp_f32_e32 v223, v223
	v_exp_f32_e32 v224, v224
	v_exp_f32_e32 v225, v225
	v_pk_add_f32 v[222:223], v[222:223], 1.0 op_sel_hi:[1,0]
	v_pk_add_f32 v[224:225], v[224:225], 1.0 op_sel_hi:[1,0]
	v_rcp_f32_e32 v222, v222
	v_rcp_f32_e32 v223, v223
	v_rcp_f32_e32 v224, v224
	v_rcp_f32_e32 v225, v225
	v_pk_mul_f32 v[218:219], v[214:215], v[222:223]
	v_pk_mul_f32 v[220:221], v[216:217], v[224:225]
	v_pk_mul_f32 v[106:107], v[106:107], v[218:219]
	v_pk_mul_f32 v[108:109], v[108:109], v[220:221]
	v_cvt_pk_bf16_f32 v110, v110, v111
	v_cvt_pk_bf16_f32 v111, v112, v113
	v_cvt_pk_bf16_f32 v112, v106, v107
	v_cvt_pk_bf16_f32 v113, v108, v109
	v_add_u32_e32 v222, 0xc0000, v195
	global_store_dwordx4 v222, v[110:113], s[70:71]
	s_add_u32 s86, s74, 0x80000
	s_addc_u32 s87, s75, 0
	global_load_dwordx4 v[162:165], v196, s[86:87]
	global_load_dwordx4 v[166:169], v196, s[86:87] offset:16
	s_add_u32 s86, s72, 0x80000
	s_addc_u32 s87, s73, 0
	s_mov_b32 exec_lo, 0xc000c000
	s_mov_b32 exec_hi, 0xc000c000
	global_store_dwordx4 v196, v[86:89], s[86:87]
	global_store_dwordx4 v196, v[82:85], s[86:87] offset:16
	s_mov_b64 exec, -1
	s_waitcnt vmcnt(2)
; __device__ __forceinline__ u32x4 pack8(const f32x4 a, const f32x4 b) { u32x4 w; w.x = cvt_pk_bf16(a[0], a[1]); w.y = cvt_pk_bf16(a[2], a[3]); w.z = cvt_pk_bf16(b[0], b[1]); w.w = cvt_pk_bf16(b[2], b[3]); return w; }
; template <int CTRL> __device__ __forceinline__ float dppf(float v) { return __builtin_bit_cast(float, __builtin_amdgcn_update_dpp(0, __builtin_bit_cast(int, v), CTRL, 0xf, 0xf, true)); }
;     __device__ __forceinline__ void operator()(const f32x4 (&acc)[2][2][4][2], const Unit& u, int wr, int wc, int fr, int fq) const {
;     ...
;                 f32x4 hv[2];
; #pragma unroll
;                 for (int n = 0; n < 2; ++n) {
;                     const f32x4 a = acc[ai][0][m][n], b = acc[ai][1][m][n];
; #pragma unroll
;                     for (int i = 0; i < 4; ++i) {
;                         const float s1 = dppf<0x111>(a[i]), s2 = dppf<0x112>(a[i]);
;                         const float p1 = fr >= 1 ? s1 : w1[n][i], p2 = fr >= 2 ? s2 : w2[n][i];
;                         const float ac = cw0[n][i] * p2 + cw1[n][i] * p1 + cw2[n][i] * a[i] + cb[n][i];
;                         hv[n][i] = gelu_tanh(ac) * b[i];
;                     }
;                 }
;                 *(u32x4*)(hh + (size_t)row * DFF + cgc) = pack8(hv[0], hv[1]);
;                 if (samp) {
;                     if (fr >= 14) { const int bs = (row - MP) >> 4; float* p = out + O_CVS + ((size_t)bs * 2 + (fr - 14)) * DFF + cgc; *(f32x4*)p = acc[ai][0][m][0]; *(f32x4*)(p + 4) = acc[ai][0][m][1]; }
	v_pk_fma_f32 v[214:215], v[66:67], v[86:87], v[74:75]
	v_pk_fma_f32 v[216:217], v[68:69], v[88:89], v[76:77]
	v_fmac_f32_dpp v214, v86, v50 row_shr:1 row_mask:0xf bank_mask:0xf
	v_fmac_f32_dpp v215, v87, v51 row_shr:1 row_mask:0xf bank_mask:0xf
	v_fmac_f32_dpp v216, v88, v52 row_shr:1 row_mask:0xf bank_mask:0xf
	v_fmac_f32_dpp v217, v89, v53 row_shr:1 row_mask:0xf bank_mask:0xf
	v_fmac_f32_dpp v214, v162, v50 row_shl:15 row_mask:0xf bank_mask:0xf
	v_fmac_f32_dpp v215, v163, v51 row_shl:15 row_mask:0xf bank_mask:0xf
	v_fmac_f32_dpp v216, v164, v52 row_shl:15 row_mask:0xf bank_mask:0xf
	v_fmac_f32_dpp v217, v165, v53 row_shl:15 row_mask:0xf bank_mask:0xf
	v_fmac_f32_dpp v214, v86, v42 row_shr:2 row_mask:0xf bank_mask:0xf
	v_fmac_f32_dpp v215, v87, v43 row_shr:2 row_mask:0xf bank_mask:0xf
	v_fmac_f32_dpp v216, v88, v44 row_shr:2 row_mask:0xf bank_mask:0xf
	v_fmac_f32_dpp v217, v89, v45 row_shr:2 row_mask:0xf bank_mask:0xf
	v_fmac_f32_dpp v214, v162, v42 row_shl:14 row_mask:0xf bank_mask:0xf
	v_fmac_f32_dpp v215, v163, v43 row_shl:14 row_mask:0xf bank_mask:0xf
	v_fmac_f32_dpp v216, v164, v44 row_shl:14 row_mask:0xf bank_mask:0xf
	v_fmac_f32_dpp v217, v165, v45 row_shl:14 row_mask:0xf bank_mask:0xf
	v_pk_mul_f32 v[218:219], v[214:215], v[226:227] op_sel_hi:[1,0]
	v_pk_mul_f32 v[220:221], v[216:217], v[226:227] op_sel_hi:[1,0]
	v_pk_mul_f32 v[222:223], v[214:215], v[228:229] op_sel_hi:[1,0]
	v_pk_mul_f32 v[224:225], v[216:217], v[228:229] op_sel_hi:[1,0]
	v_pk_fma_f32 v[218:219], v[214:215], v[218:219], 1.0 op_sel_hi:[1,1,0]
	v_pk_fma_f32 v[220:221], v[216:217], v[220:221], 1.0 op_sel_hi:[1,1,0]
	v_pk_mul_f32 v[222:223], v[222:223], v[218:219] neg_lo:[0,1] neg_hi:[0,1]
	v_pk_mul_f32 v[224:225], v[224:225], v[220:221] neg_lo:[0,1] neg_hi:[0,1]
	v_pk_mul_f32 v[222:223], v[222:223], v[230:231] op_sel_hi:[1,0]
	v_pk_mul_f32 v[224:225], v[224:225], v[230:231] op_sel_hi:[1,0]
	v_exp_f32_e32 v222, v222
	v_exp_f32_e32 v223, v223
	v_exp_f32_e32 v224, v224
	v_exp_f32_e32 v225, v225
	v_pk_add_f32 v[222:223], v[222:223], 1.0 op_sel_hi:[1,0]
	v_pk_add_f32 v[224:225], v[224:225], 1.0 op_sel_hi:[1,0]
	v_rcp_f32_e32 v222, v222
	v_rcp_f32_e32 v223, v223
	v_rcp_f32_e32 v224, v224
	v_rcp_f32_e32 v225, v225
	v_pk_mul_f32 v[218:219], v[214:215], v[222:223]
	v_pk_mul_f32 v[220:221], v[216:217], v[224:225]
	v_pk_mul_f32 v[94:95], v[94:95], v[218:219]
	v_pk_mul_f32 v[96:97], v[96:97], v[220:221]
	v_pk_fma_f32 v[214:215], v[70:71], v[82:83], v[78:79]
	v_pk_fma_f32 v[216:217], v[72:73], v[84:85], v[80:81]
	v_fmac_f32_dpp v214, v82, v54 row_shr:1 row_mask:0xf bank_mask:0xf
	v_fmac_f32_dpp v215, v83, v55 row_shr:1 row_mask:0xf bank_mask:0xf
	v_fmac_f32_dpp v216, v84, v56 row_shr:1 row_mask:0xf bank_mask:0xf
	v_fmac_f32_dpp v217, v85, v57 row_shr:1 row_mask:0xf bank_mask:0xf
	v_fmac_f32_dpp v214, v166, v54 row_shl:15 row_mask:0xf bank_mask:0xf
	v_fmac_f32_dpp v215, v167, v55 row_shl:15 row_mask:0xf bank_mask:0xf
	v_fmac_f32_dpp v216, v168, v56 row_shl:15 row_mask:0xf bank_mask:0xf
	v_fmac_f32_dpp v217, v169, v57 row_shl:15 row_mask:0xf bank_mask:0xf
	v_fmac_f32_dpp v214, v82, v46 row_shr:2 row_mask:0xf bank_mask:0xf
	v_fmac_f32_dpp v215, v83, v47 row_shr:2 row_mask:0xf bank_mask:0xf
	v_fmac_f32_dpp v216, v84, v48 row_shr:2 row_mask:0xf bank_mask:0xf
	v_fmac_f32_dpp v217, v85, v49 row_shr:2 row_mask:0xf bank_mask:0xf
	v_fmac_f32_dpp v214, v166, v46 row_shl:14 row_mask:0xf bank_mask:0xf
	v_fmac_f32_dpp v215, v167, v47 row_shl:14 row_mask:0xf bank_mask:0xf
	v_fmac_f32_dpp v216, v168, v48 row_shl:14 row_mask:0xf bank_mask:0xf
	v_fmac_f32_dpp v217, v169, v49 row_shl:14 row_mask:0xf bank_mask:0xf
	v_pk_mul_f32 v[218:219], v[214:215], v[226:227] op_sel_hi:[1,0]
	v_pk_mul_f32 v[220:221], v[216:217], v[226:227] op_sel_hi:[1,0]
	v_pk_mul_f32 v[222:223], v[214:215], v[228:229] op_sel_hi:[1,0]
	v_pk_mul_f32 v[224:225], v[216:217], v[228:229] op_sel_hi:[1,0]
	v_pk_fma_f32 v[218:219], v[214:215], v[218:219], 1.0 op_sel_hi:[1,1,0]
	v_pk_fma_f32 v[220:221], v[216:217], v[220:221], 1.0 op_sel_hi:[1,1,0]
	v_pk_mul_f32 v[222:223], v[222:223], v[218:219] neg_lo:[0,1] neg_hi:[0,1]
	v_pk_mul_f32 v[224:225], v[224:225], v[220:221] neg_lo:[0,1] neg_hi:[0,1]
	v_pk_mul_f32 v[222:223], v[222:223], v[230:231] op_sel_hi:[1,0]
	v_pk_mul_f32 v[224:225], v[224:225], v[230:231] op_sel_hi:[1,0]
	v_exp_f32_e32 v222, v222
	v_exp_f32_e32 v223, v223
	v_exp_f32_e32 v224, v224
	v_exp_f32_e32 v225, v225
	v_pk_add_f32 v[222:223], v[222:223], 1.0 op_sel_hi:[1,0]
	v_pk_add_f32 v[224:225], v[224:225], 1.0 op_sel_hi:[1,0]
	v_rcp_f32_e32 v222, v222
	v_rcp_f32_e32 v223, v223
	v_rcp_f32_e32 v224, v224
	v_rcp_f32_e32 v225, v225
	v_pk_mul_f32 v[218:219], v[214:215], v[222:223]
	v_pk_mul_f32 v[220:221], v[216:217], v[224:225]
	v_pk_mul_f32 v[90:91], v[90:91], v[218:219]
	v_pk_mul_f32 v[92:93], v[92:93], v[220:221]
	v_cvt_pk_bf16_f32 v94, v94, v95
	v_cvt_pk_bf16_f32 v95, v96, v97
	v_cvt_pk_bf16_f32 v96, v90, v91
	v_cvt_pk_bf16_f32 v97, v92, v93
	v_add_u32_e32 v222, 0x200000, v195
	global_store_dwordx4 v222, v[94:97], s[70:71]
	s_add_u32 s86, s74, 0x90000
	s_addc_u32 s87, s75, 0
	global_load_dwordx4 v[162:165], v196, s[86:87]
	global_load_dwordx4 v[166:169], v196, s[86:87] offset:16
	s_add_u32 s86, s72, 0x90000
	s_addc_u32 s87, s73, 0
	s_mov_b32 exec_lo, 0xc000c000
	s_mov_b32 exec_hi, 0xc000c000
	global_store_dwordx4 v196, v[38:41], s[86:87]
	global_store_dwordx4 v196, v[34:37], s[86:87] offset:16
	s_mov_b64 exec, -1
	s_waitcnt vmcnt(2)
; __device__ __forceinline__ u32x4 pack8(const f32x4 a, const f32x4 b) { u32x4 w; w.x = cvt_pk_bf16(a[0], a[1]); w.y = cvt_pk_bf16(a[2], a[3]); w.z = cvt_pk_bf16(b[0], b[1]); w.w = cvt_pk_bf16(b[2], b[3]); return w; }
; template <int CTRL> __device__ __forceinline__ float dppf(float v) { return __builtin_bit_cast(float, __builtin_amdgcn_update_dpp(0, __builtin_bit_cast(int, v), CTRL, 0xf, 0xf, true)); }
;     __device__ __forceinline__ void operator()(const f32x4 (&acc)[2][2][4][2], const Unit& u, int wr, int wc, int fr, int fq) const {
;     ...
;                 f32x4 hv[2];
; #pragma unroll
;                 for (int n = 0; n < 2; ++n) {
;                     const f32x4 a = acc[ai][0][m][n], b = acc[ai][1][m][n];
; #pragma unroll
;                     for (int i = 0; i < 4; ++i) {
;                         const float s1 = dppf<0x111>(a[i]), s2 = dppf<0x112>(a[i]);
;                         const float p1 = fr >= 1 ? s1 : w1[n][i], p2 = fr >= 2 ? s2 : w2[n][i];
;                         const float ac = cw0[n][i] * p2 + cw1[n][i] * p1 + cw2[n][i] * a[i] + cb[n][i];
;                         hv[n][i] = gelu_tanh(ac) * b[i];
;                     }
;                 }
;                 *(u32x4*)(hh + (size_t)row * DFF + cgc) = pack8(hv[0], hv[1]);
;                 if (samp) {
;                     if (fr >= 14) { const int bs = (row - MP) >> 4; float* p = out + O_CVS + ((size_t)bs * 2 + (fr - 14)) * DFF + cgc; *(f32x4*)p = acc[ai][0][m][0]; *(f32x4*)(p + 4) = acc[ai][0][m][1]; }
	v_pk_fma_f32 v[214:215], v[66:67], v[38:39], v[74:75]
	v_pk_fma_f32 v[216:217], v[68:69], v[40:41], v[76:77]
	v_fmac_f32_dpp v214, v38, v50 row_shr:1 row_mask:0xf bank_mask:0xf
	v_fmac_f32_dpp v215, v39, v51 row_shr:1 row_mask:0xf bank_mask:0xf
	v_fmac_f32_dpp v216, v40, v52 row_shr:1 row_mask:0xf bank_mask:0xf
	v_fmac_f32_dpp v217, v41, v53 row_shr:1 row_mask:0xf bank_mask:0xf
	v_fmac_f32_dpp v214, v162, v50 row_shl:15 row_mask:0xf bank_mask:0xf
	v_fmac_f32_dpp v215, v163, v51 row_shl:15 row_mask:0xf bank_mask:0xf
	v_fmac_f32_dpp v216, v164, v52 row_shl:15 row_mask:0xf bank_mask:0xf
	v_fmac_f32_dpp v217, v165, v53 row_shl:15 row_mask:0xf bank_mask:0xf
	v_fmac_f32_dpp v214, v38, v42 row_shr:2 row_mask:0xf bank_mask:0xf
	v_fmac_f32_dpp v215, v39, v43 row_shr:2 row_mask:0xf bank_mask:0xf
	v_fmac_f32_dpp v216, v40, v44 row_shr:2 row_mask:0xf bank_mask:0xf
	v_fmac_f32_dpp v217, v41, v45 row_shr:2 row_mask:0xf bank_mask:0xf
	v_fmac_f32_dpp v214, v162, v42 row_shl:14 row_mask:0xf bank_mask:0xf
	v_fmac_f32_dpp v215, v163, v43 row_shl:14 row_mask:0xf bank_mask:0xf
	v_fmac_f32_dpp v216, v164, v44 row_shl:14 row_mask:0xf bank_mask:0xf
	v_fmac_f32_dpp v217, v165, v45 row_shl:14 row_mask:0xf bank_mask:0xf
	v_pk_mul_f32 v[218:219], v[214:215], v[226:227] op_sel_hi:[1,0]
	v_pk_mul_f32 v[220:221], v[216:217], v[226:227] op_sel_hi:[1,0]
	v_pk_mul_f32 v[222:223], v[214:215], v[228:229] op_sel_hi:[1,0]
	v_pk_mul_f32 v[224:225], v[216:217], v[228:229] op_sel_hi:[1,0]
	v_pk_fma_f32 v[218:219], v[214:215], v[218:219], 1.0 op_sel_hi:[1,1,0]
	v_pk_fma_f32 v[220:221], v[216:217], v[220:221], 1.0 op_sel_hi:[1,1,0]
	v_pk_mul_f32 v[222:223], v[222:223], v[218:219] neg_lo:[0,1] neg_hi:[0,1]
	v_pk_mul_f32 v[224:225], v[224:225], v[220:221] neg_lo:[0,1] neg_hi:[0,1]
	v_pk_mul_f32 v[222:223], v[222:223], v[230:231] op_sel_hi:[1,0]
	v_pk_mul_f32 v[224:225], v[224:225], v[230:231] op_sel_hi:[1,0]
	v_exp_f32_e32 v222, v222
	v_exp_f32_e32 v223, v223
	v_exp_f32_e32 v224, v224
	v_exp_f32_e32 v225, v225
	v_pk_add_f32 v[222:223], v[222:223], 1.0 op_sel_hi:[1,0]
	v_pk_add_f32 v[224:225], v[224:225], 1.0 op_sel_hi:[1,0]
	v_rcp_f32_e32 v222, v222
	v_rcp_f32_e32 v223, v223
	v_rcp_f32_e32 v224, v224
	v_rcp_f32_e32 v225, v225
	v_pk_mul_f32 v[218:219], v[214:215], v[222:223]
	v_pk_mul_f32 v[220:221], v[216:217], v[224:225]
	v_pk_mul_f32 v[62:63], v[62:63], v[218:219]
	v_pk_mul_f32 v[64:65], v[64:65], v[220:221]
	v_pk_fma_f32 v[214:215], v[70:71], v[34:35], v[78:79]
	v_pk_fma_f32 v[216:217], v[72:73], v[36:37], v[80:81]
	v_fmac_f32_dpp v214, v34, v54 row_shr:1 row_mask:0xf bank_mask:0xf
	v_fmac_f32_dpp v215, v35, v55 row_shr:1 row_mask:0xf bank_mask:0xf
	v_fmac_f32_dpp v216, v36, v56 row_shr:1 row_mask:0xf bank_mask:0xf
	v_fmac_f32_dpp v217, v37, v57 row_shr:1 row_mask:0xf bank_mask:0xf
	v_fmac_f32_dpp v214, v166, v54 row_shl:15 row_mask:0xf bank_mask:0xf
	v_fmac_f32_dpp v215, v167, v55 row_shl:15 row_mask:0xf bank_mask:0xf
	v_fmac_f32_dpp v216, v168, v56 row_shl:15 row_mask:0xf bank_mask:0xf
	v_fmac_f32_dpp v217, v169, v57 row_shl:15 row_mask:0xf bank_mask:0xf
	v_fmac_f32_dpp v214, v34, v46 row_shr:2 row_mask:0xf bank_mask:0xf
	v_fmac_f32_dpp v215, v35, v47 row_shr:2 row_mask:0xf bank_mask:0xf
	v_fmac_f32_dpp v216, v36, v48 row_shr:2 row_mask:0xf bank_mask:0xf
	v_fmac_f32_dpp v217, v37, v49 row_shr:2 row_mask:0xf bank_mask:0xf
	v_fmac_f32_dpp v214, v166, v46 row_shl:14 row_mask:0xf bank_mask:0xf
	v_fmac_f32_dpp v215, v167, v47 row_shl:14 row_mask:0xf bank_mask:0xf
	v_fmac_f32_dpp v216, v168, v48 row_shl:14 row_mask:0xf bank_mask:0xf
	v_fmac_f32_dpp v217, v169, v49 row_shl:14 row_mask:0xf bank_mask:0xf
	v_pk_mul_f32 v[218:219], v[214:215], v[226:227] op_sel_hi:[1,0]
	v_pk_mul_f32 v[220:221], v[216:217], v[226:227] op_sel_hi:[1,0]
	v_pk_mul_f32 v[222:223], v[214:215], v[228:229] op_sel_hi:[1,0]
	v_pk_mul_f32 v[224:225], v[216:217], v[228:229] op_sel_hi:[1,0]
	v_pk_fma_f32 v[218:219], v[214:215], v[218:219], 1.0 op_sel_hi:[1,1,0]
	v_pk_fma_f32 v[220:221], v[216:217], v[220:221], 1.0 op_sel_hi:[1,1,0]
	v_pk_mul_f32 v[222:223], v[222:223], v[218:219] neg_lo:[0,1] neg_hi:[0,1]
	v_pk_mul_f32 v[224:225], v[224:225], v[220:221] neg_lo:[0,1] neg_hi:[0,1]
	v_pk_mul_f32 v[222:223], v[222:223], v[230:231] op_sel_hi:[1,0]
	v_pk_mul_f32 v[224:225], v[224:225], v[230:231] op_sel_hi:[1,0]
	v_exp_f32_e32 v222, v222
	v_exp_f32_e32 v223, v223
	v_exp_f32_e32 v224, v224
	v_exp_f32_e32 v225, v225
	v_pk_add_f32 v[222:223], v[222:223], 1.0 op_sel_hi:[1,0]
	v_pk_add_f32 v[224:225], v[224:225], 1.0 op_sel_hi:[1,0]
	v_rcp_f32_e32 v222, v222
	v_rcp_f32_e32 v223, v223
	v_rcp_f32_e32 v224, v224
	v_rcp_f32_e32 v225, v225
	v_pk_mul_f32 v[218:219], v[214:215], v[222:223]
	v_pk_mul_f32 v[220:221], v[216:217], v[224:225]
	v_pk_mul_f32 v[58:59], v[58:59], v[218:219]
	v_pk_mul_f32 v[60:61], v[60:61], v[220:221]
	v_cvt_pk_bf16_f32 v62, v62, v63
	v_cvt_pk_bf16_f32 v63, v64, v65
	v_cvt_pk_bf16_f32 v64, v58, v59
	v_cvt_pk_bf16_f32 v65, v60, v61
	v_add_u32_e32 v222, 0x240000, v195
	global_store_dwordx4 v222, v[62:65], s[70:71]
	s_add_u32 s86, s74, 0xa0000
	s_addc_u32 s87, s75, 0
	global_load_dwordx4 v[162:165], v196, s[86:87]
	global_load_dwordx4 v[166:169], v196, s[86:87] offset:16
	s_add_u32 s86, s72, 0xa0000
	s_addc_u32 s87, s73, 0
	s_mov_b32 exec_lo, 0xc000c000
	s_mov_b32 exec_hi, 0xc000c000
	global_store_dwordx4 v196, v[22:25], s[86:87]
	global_store_dwordx4 v196, v[18:21], s[86:87] offset:16
	s_mov_b64 exec, -1
	s_waitcnt vmcnt(2)
; __device__ __forceinline__ u32x4 pack8(const f32x4 a, const f32x4 b) { u32x4 w; w.x = cvt_pk_bf16(a[0], a[1]); w.y = cvt_pk_bf16(a[2], a[3]); w.z = cvt_pk_bf16(b[0], b[1]); w.w = cvt_pk_bf16(b[2], b[3]); return w; }
; template <int CTRL> __device__ __forceinline__ float dppf(float v) { return __builtin_bit_cast(float, __builtin_amdgcn_update_dpp(0, __builtin_bit_cast(int, v), CTRL, 0xf, 0xf, true)); }
;     __device__ __forceinline__ void operator()(const f32x4 (&acc)[2][2][4][2], const Unit& u, int wr, int wc, int fr, int fq) const {
;     ...
;                 f32x4 hv[2];
; #pragma unroll
;                 for (int n = 0; n < 2; ++n) {
;                     const f32x4 a = acc[ai][0][m][n], b = acc[ai][1][m][n];
; #pragma unroll
;                     for (int i = 0; i < 4; ++i) {
;                         const float s1 = dppf<0x111>(a[i]), s2 = dppf<0x112>(a[i]);
;                         const float p1 = fr >= 1 ? s1 : w1[n][i], p2 = fr >= 2 ? s2 : w2[n][i];
;                         const float ac = cw0[n][i] * p2 + cw1[n][i] * p1 + cw2[n][i] * a[i] + cb[n][i];
;                         hv[n][i] = gelu_tanh(ac) * b[i];
;                     }
;                 }
;                 *(u32x4*)(hh + (size_t)row * DFF + cgc) = pack8(hv[0], hv[1]);
;                 if (samp) {
;                     if (fr >= 14) { const int bs = (row - MP) >> 4; float* p = out + O_CVS + ((size_t)bs * 2 + (fr - 14)) * DFF + cgc; *(f32x4*)p = acc[ai][0][m][0]; *(f32x4*)(p + 4) = acc[ai][0][m][1]; }
	v_pk_fma_f32 v[214:215], v[66:67], v[22:23], v[74:75]
	v_pk_fma_f32 v[216:217], v[68:69], v[24:25], v[76:77]
	v_fmac_f32_dpp v214, v22, v50 row_shr:1 row_mask:0xf bank_mask:0xf
	v_fmac_f32_dpp v215, v23, v51 row_shr:1 row_mask:0xf bank_mask:0xf
	v_fmac_f32_dpp v216, v24, v52 row_shr:1 row_mask:0xf bank_mask:0xf
	v_fmac_f32_dpp v217, v25, v53 row_shr:1 row_mask:0xf bank_mask:0xf
	v_fmac_f32_dpp v214, v162, v50 row_shl:15 row_mask:0xf bank_mask:0xf
	v_fmac_f32_dpp v215, v163, v51 row_shl:15 row_mask:0xf bank_mask:0xf
	v_fmac_f32_dpp v216, v164, v52 row_shl:15 row_mask:0xf bank_mask:0xf
	v_fmac_f32_dpp v217, v165, v53 row_shl:15 row_mask:0xf bank_mask:0xf
	v_fmac_f32_dpp v214, v22, v42 row_shr:2 row_mask:0xf bank_mask:0xf
	v_fmac_f32_dpp v215, v23, v43 row_shr:2 row_mask:0xf bank_mask:0xf
	v_fmac_f32_dpp v216, v24, v44 row_shr:2 row_mask:0xf bank_mask:0xf
	v_fmac_f32_dpp v217, v25, v45 row_shr:2 row_mask:0xf bank_mask:0xf
	v_fmac_f32_dpp v214, v162, v42 row_shl:14 row_mask:0xf bank_mask:0xf
	v_fmac_f32_dpp v215, v163, v43 row_shl:14 row_mask:0xf bank_mask:0xf
	v_fmac_f32_dpp v216, v164, v44 row_shl:14 row_mask:0xf bank_mask:0xf
	v_fmac_f32_dpp v217, v165, v45 row_shl:14 row_mask:0xf bank_mask:0xf
	v_pk_mul_f32 v[218:219], v[214:215], v[226:227] op_sel_hi:[1,0]
	v_pk_mul_f32 v[220:221], v[216:217], v[226:227] op_sel_hi:[1,0]
	v_pk_mul_f32 v[222:223], v[214:215], v[228:229] op_sel_hi:[1,0]
	v_pk_mul_f32 v[224:225], v[216:217], v[228:229] op_sel_hi:[1,0]
	v_pk_fma_f32 v[218:219], v[214:215], v[218:219], 1.0 op_sel_hi:[1,1,0]
	v_pk_fma_f32 v[220:221], v[216:217], v[220:221], 1.0 op_sel_hi:[1,1,0]
	v_pk_mul_f32 v[222:223], v[222:223], v[218:219] neg_lo:[0,1] neg_hi:[0,1]
	v_pk_mul_f32 v[224:225], v[224:225], v[220:221] neg_lo:[0,1] neg_hi:[0,1]
	v_pk_mul_f32 v[222:223], v[222:223], v[230:231] op_sel_hi:[1,0]
	v_pk_mul_f32 v[224:225], v[224:225], v[230:231] op_sel_hi:[1,0]
	v_exp_f32_e32 v222, v222
	v_exp_f32_e32 v223, v223
	v_exp_f32_e32 v224, v224
	v_exp_f32_e32 v225, v225
	v_pk_add_f32 v[222:223], v[222:223], 1.0 op_sel_hi:[1,0]
	v_pk_add_f32 v[224:225], v[224:225], 1.0 op_sel_hi:[1,0]
	v_rcp_f32_e32 v222, v222
	v_rcp_f32_e32 v223, v223
	v_rcp_f32_e32 v224, v224
	v_rcp_f32_e32 v225, v225
	v_pk_mul_f32 v[218:219], v[214:215], v[222:223]
	v_pk_mul_f32 v[220:221], v[216:217], v[224:225]
	v_pk_mul_f32 v[30:31], v[30:31], v[218:219]
	v_pk_mul_f32 v[32:33], v[32:33], v[220:221]
	v_pk_fma_f32 v[214:215], v[70:71], v[18:19], v[78:79]
	v_pk_fma_f32 v[216:217], v[72:73], v[20:21], v[80:81]
	v_fmac_f32_dpp v214, v18, v54 row_shr:1 row_mask:0xf bank_mask:0xf
	v_fmac_f32_dpp v215, v19, v55 row_shr:1 row_mask:0xf bank_mask:0xf
	v_fmac_f32_dpp v216, v20, v56 row_shr:1 row_mask:0xf bank_mask:0xf
	v_fmac_f32_dpp v217, v21, v57 row_shr:1 row_mask:0xf bank_mask:0xf
	v_fmac_f32_dpp v214, v166, v54 row_shl:15 row_mask:0xf bank_mask:0xf
	v_fmac_f32_dpp v215, v167, v55 row_shl:15 row_mask:0xf bank_mask:0xf
	v_fmac_f32_dpp v216, v168, v56 row_shl:15 row_mask:0xf bank_mask:0xf
	v_fmac_f32_dpp v217, v169, v57 row_shl:15 row_mask:0xf bank_mask:0xf
	v_fmac_f32_dpp v214, v18, v46 row_shr:2 row_mask:0xf bank_mask:0xf
	v_fmac_f32_dpp v215, v19, v47 row_shr:2 row_mask:0xf bank_mask:0xf
	v_fmac_f32_dpp v216, v20, v48 row_shr:2 row_mask:0xf bank_mask:0xf
	v_fmac_f32_dpp v217, v21, v49 row_shr:2 row_mask:0xf bank_mask:0xf
	v_fmac_f32_dpp v214, v166, v46 row_shl:14 row_mask:0xf bank_mask:0xf
	v_fmac_f32_dpp v215, v167, v47 row_shl:14 row_mask:0xf bank_mask:0xf
	v_fmac_f32_dpp v216, v168, v48 row_shl:14 row_mask:0xf bank_mask:0xf
	v_fmac_f32_dpp v217, v169, v49 row_shl:14 row_mask:0xf bank_mask:0xf
	v_pk_mul_f32 v[218:219], v[214:215], v[226:227] op_sel_hi:[1,0]
	v_pk_mul_f32 v[220:221], v[216:217], v[226:227] op_sel_hi:[1,0]
	v_pk_mul_f32 v[222:223], v[214:215], v[228:229] op_sel_hi:[1,0]
	v_pk_mul_f32 v[224:225], v[216:217], v[228:229] op_sel_hi:[1,0]
	v_pk_fma_f32 v[218:219], v[214:215], v[218:219], 1.0 op_sel_hi:[1,1,0]
	v_pk_fma_f32 v[220:221], v[216:217], v[220:221], 1.0 op_sel_hi:[1,1,0]
	v_pk_mul_f32 v[222:223], v[222:223], v[218:219] neg_lo:[0,1] neg_hi:[0,1]
	v_pk_mul_f32 v[224:225], v[224:225], v[220:221] neg_lo:[0,1] neg_hi:[0,1]
	v_pk_mul_f32 v[222:223], v[222:223], v[230:231] op_sel_hi:[1,0]
	v_pk_mul_f32 v[224:225], v[224:225], v[230:231] op_sel_hi:[1,0]
	v_exp_f32_e32 v222, v222
	v_exp_f32_e32 v223, v223
	v_exp_f32_e32 v224, v224
	v_exp_f32_e32 v225, v225
	v_pk_add_f32 v[222:223], v[222:223], 1.0 op_sel_hi:[1,0]
	v_pk_add_f32 v[224:225], v[224:225], 1.0 op_sel_hi:[1,0]
	v_rcp_f32_e32 v222, v222
	v_rcp_f32_e32 v223, v223
	v_rcp_f32_e32 v224, v224
	v_rcp_f32_e32 v225, v225
	v_pk_mul_f32 v[218:219], v[214:215], v[222:223]
	v_pk_mul_f32 v[220:221], v[216:217], v[224:225]
	v_pk_mul_f32 v[26:27], v[26:27], v[218:219]
	v_pk_mul_f32 v[28:29], v[28:29], v[220:221]
	v_cvt_pk_bf16_f32 v30, v30, v31
	v_cvt_pk_bf16_f32 v31, v32, v33
	v_cvt_pk_bf16_f32 v32, v26, v27
	v_cvt_pk_bf16_f32 v33, v28, v29
	v_add_u32_e32 v222, 0x280000, v195
	global_store_dwordx4 v222, v[30:33], s[70:71]
	s_add_u32 s86, s74, 0xb0000
	s_addc_u32 s87, s75, 0
	global_load_dwordx4 v[162:165], v196, s[86:87]
	global_load_dwordx4 v[166:169], v196, s[86:87] offset:16
	s_add_u32 s86, s72, 0xb0000
	s_addc_u32 s87, s73, 0
	s_mov_b32 exec_lo, 0xc000c000
	s_mov_b32 exec_hi, 0xc000c000
	global_store_dwordx4 v196, v[6:9], s[86:87]
	global_store_dwordx4 v196, v[2:5], s[86:87] offset:16
	s_mov_b64 exec, -1
	s_waitcnt vmcnt(2)
; __device__ __forceinline__ u32x4 pack8(const f32x4 a, const f32x4 b) { u32x4 w; w.x = cvt_pk_bf16(a[0], a[1]); w.y = cvt_pk_bf16(a[2], a[3]); w.z = cvt_pk_bf16(b[0], b[1]); w.w = cvt_pk_bf16(b[2], b[3]); return w; }
; template <int CTRL> __device__ __forceinline__ float dppf(float v) { return __builtin_bit_cast(float, __builtin_amdgcn_update_dpp(0, __builtin_bit_cast(int, v), CTRL, 0xf, 0xf, true)); }
;     __device__ __forceinline__ void operator()(const f32x4 (&acc)[2][2][4][2], const Unit& u, int wr, int wc, int fr, int fq) const {
;     ...
;                 f32x4 hv[2];
; #pragma unroll
;                 for (int n = 0; n < 2; ++n) {
;                     const f32x4 a = acc[ai][0][m][n], b = acc[ai][1][m][n];
; #pragma unroll
;                     for (int i = 0; i < 4; ++i) {
;                         const float s1 = dppf<0x111>(a[i]), s2 = dppf<0x112>(a[i]);
;                         const float p1 = fr >= 1 ? s1 : w1[n][i], p2 = fr >= 2 ? s2 : w2[n][i];
;                         const float ac = cw0[n][i] * p2 + cw1[n][i] * p1 + cw2[n][i] * a[i] + cb[n][i];
;                         hv[n][i] = gelu_tanh(ac) * b[i];
;                     }
;                 }
;                 *(u32x4*)(hh + (size_t)row * DFF + cgc) = pack8(hv[0], hv[1]);
	v_pk_fma_f32 v[214:215], v[66:67], v[6:7], v[74:75]
	v_pk_fma_f32 v[216:217], v[68:69], v[8:9], v[76:77]
	v_fmac_f32_dpp v214, v6, v50 row_shr:1 row_mask:0xf bank_mask:0xf
	v_fmac_f32_dpp v215, v7, v51 row_shr:1 row_mask:0xf bank_mask:0xf
	v_fmac_f32_dpp v216, v8, v52 row_shr:1 row_mask:0xf bank_mask:0xf
	v_fmac_f32_dpp v217, v9, v53 row_shr:1 row_mask:0xf bank_mask:0xf
	v_fmac_f32_dpp v214, v162, v50 row_shl:15 row_mask:0xf bank_mask:0xf
	v_fmac_f32_dpp v215, v163, v51 row_shl:15 row_mask:0xf bank_mask:0xf
	v_fmac_f32_dpp v216, v164, v52 row_shl:15 row_mask:0xf bank_mask:0xf
	v_fmac_f32_dpp v217, v165, v53 row_shl:15 row_mask:0xf bank_mask:0xf
	v_fmac_f32_dpp v214, v6, v42 row_shr:2 row_mask:0xf bank_mask:0xf
	v_fmac_f32_dpp v215, v7, v43 row_shr:2 row_mask:0xf bank_mask:0xf
	v_fmac_f32_dpp v216, v8, v44 row_shr:2 row_mask:0xf bank_mask:0xf
	v_fmac_f32_dpp v217, v9, v45 row_shr:2 row_mask:0xf bank_mask:0xf
	v_fmac_f32_dpp v214, v162, v42 row_shl:14 row_mask:0xf bank_mask:0xf
	v_fmac_f32_dpp v215, v163, v43 row_shl:14 row_mask:0xf bank_mask:0xf
	v_fmac_f32_dpp v216, v164, v44 row_shl:14 row_mask:0xf bank_mask:0xf
	v_fmac_f32_dpp v217, v165, v45 row_shl:14 row_mask:0xf bank_mask:0xf
	v_pk_mul_f32 v[218:219], v[214:215], v[226:227] op_sel_hi:[1,0]
	v_pk_mul_f32 v[220:221], v[216:217], v[226:227] op_sel_hi:[1,0]
	v_pk_mul_f32 v[222:223], v[214:215], v[228:229] op_sel_hi:[1,0]
	v_pk_mul_f32 v[224:225], v[216:217], v[228:229] op_sel_hi:[1,0]
	v_pk_fma_f32 v[218:219], v[214:215], v[218:219], 1.0 op_sel_hi:[1,1,0]
	v_pk_fma_f32 v[220:221], v[216:217], v[220:221], 1.0 op_sel_hi:[1,1,0]
	v_pk_mul_f32 v[222:223], v[222:223], v[218:219] neg_lo:[0,1] neg_hi:[0,1]
	v_pk_mul_f32 v[224:225], v[224:225], v[220:221] neg_lo:[0,1] neg_hi:[0,1]
	v_pk_mul_f32 v[222:223], v[222:223], v[230:231] op_sel_hi:[1,0]
	v_pk_mul_f32 v[224:225], v[224:225], v[230:231] op_sel_hi:[1,0]
	v_exp_f32_e32 v222, v222
	v_exp_f32_e32 v223, v223
	v_exp_f32_e32 v224, v224
	v_exp_f32_e32 v225, v225
	v_pk_add_f32 v[222:223], v[222:223], 1.0 op_sel_hi:[1,0]
	v_pk_add_f32 v[224:225], v[224:225], 1.0 op_sel_hi:[1,0]
	v_rcp_f32_e32 v222, v222
	v_rcp_f32_e32 v223, v223
	v_rcp_f32_e32 v224, v224
	v_rcp_f32_e32 v225, v225
	v_pk_mul_f32 v[218:219], v[214:215], v[222:223]
	v_pk_mul_f32 v[220:221], v[216:217], v[224:225]
	v_pk_mul_f32 v[14:15], v[14:15], v[218:219]
	v_pk_mul_f32 v[16:17], v[16:17], v[220:221]
	v_pk_fma_f32 v[214:215], v[70:71], v[2:3], v[78:79]
	v_pk_fma_f32 v[216:217], v[72:73], v[4:5], v[80:81]
	v_fmac_f32_dpp v214, v2, v54 row_shr:1 row_mask:0xf bank_mask:0xf
	v_fmac_f32_dpp v215, v3, v55 row_shr:1 row_mask:0xf bank_mask:0xf
	v_fmac_f32_dpp v216, v4, v56 row_shr:1 row_mask:0xf bank_mask:0xf
	v_fmac_f32_dpp v217, v5, v57 row_shr:1 row_mask:0xf bank_mask:0xf
	v_fmac_f32_dpp v214, v166, v54 row_shl:15 row_mask:0xf bank_mask:0xf
	v_fmac_f32_dpp v215, v167, v55 row_shl:15 row_mask:0xf bank_mask:0xf
	v_fmac_f32_dpp v216, v168, v56 row_shl:15 row_mask:0xf bank_mask:0xf
	v_fmac_f32_dpp v217, v169, v57 row_shl:15 row_mask:0xf bank_mask:0xf
	v_fmac_f32_dpp v214, v2, v46 row_shr:2 row_mask:0xf bank_mask:0xf
	v_fmac_f32_dpp v215, v3, v47 row_shr:2 row_mask:0xf bank_mask:0xf
	v_fmac_f32_dpp v216, v4, v48 row_shr:2 row_mask:0xf bank_mask:0xf
	v_fmac_f32_dpp v217, v5, v49 row_shr:2 row_mask:0xf bank_mask:0xf
	v_fmac_f32_dpp v214, v166, v46 row_shl:14 row_mask:0xf bank_mask:0xf
	v_fmac_f32_dpp v215, v167, v47 row_shl:14 row_mask:0xf bank_mask:0xf
	v_fmac_f32_dpp v216, v168, v48 row_shl:14 row_mask:0xf bank_mask:0xf
	v_fmac_f32_dpp v217, v169, v49 row_shl:14 row_mask:0xf bank_mask:0xf
	v_pk_mul_f32 v[218:219], v[214:215], v[226:227] op_sel_hi:[1,0]
	v_pk_mul_f32 v[220:221], v[216:217], v[226:227] op_sel_hi:[1,0]
	v_pk_mul_f32 v[222:223], v[214:215], v[228:229] op_sel_hi:[1,0]
	v_pk_mul_f32 v[224:225], v[216:217], v[228:229] op_sel_hi:[1,0]
	v_pk_fma_f32 v[218:219], v[214:215], v[218:219], 1.0 op_sel_hi:[1,1,0]
	v_pk_fma_f32 v[220:221], v[216:217], v[220:221], 1.0 op_sel_hi:[1,1,0]
	v_pk_mul_f32 v[222:223], v[222:223], v[218:219] neg_lo:[0,1] neg_hi:[0,1]
	v_pk_mul_f32 v[224:225], v[224:225], v[220:221] neg_lo:[0,1] neg_hi:[0,1]
	v_pk_mul_f32 v[222:223], v[222:223], v[230:231] op_sel_hi:[1,0]
	v_pk_mul_f32 v[224:225], v[224:225], v[230:231] op_sel_hi:[1,0]
	v_exp_f32_e32 v222, v222
	v_exp_f32_e32 v223, v223
	v_exp_f32_e32 v224, v224
	v_exp_f32_e32 v225, v225
	v_pk_add_f32 v[222:223], v[222:223], 1.0 op_sel_hi:[1,0]
	v_pk_add_f32 v[224:225], v[224:225], 1.0 op_sel_hi:[1,0]
	v_rcp_f32_e32 v222, v222
	v_rcp_f32_e32 v223, v223
	v_rcp_f32_e32 v224, v224
	v_rcp_f32_e32 v225, v225
	v_pk_mul_f32 v[218:219], v[214:215], v[222:223]
	v_pk_mul_f32 v[220:221], v[216:217], v[224:225]
	v_pk_mul_f32 v[10:11], v[10:11], v[218:219]
	v_pk_mul_f32 v[12:13], v[12:13], v[220:221]
	v_cvt_pk_bf16_f32 v14, v14, v15
	v_cvt_pk_bf16_f32 v15, v16, v17
	v_cvt_pk_bf16_f32 v16, v10, v11
	v_cvt_pk_bf16_f32 v17, v12, v13
	v_add_u32_e32 v222, 0x2c0000, v195
	global_store_dwordx4 v222, v[14:17], s[70:71]
